# s_setprio pairs removed from the 7 streamed GEMM K-loops (on top of SwiGLU load hoist and VALU softmax denominator)
# speedup vs baseline: 1.0209x; 1.0083x over previous
.LBB0_167:
	s_add_u32 s72, s60, 0xfffc0080
	s_addc_u32 s73, s61, -1
	s_add_i32 s76, 16, 0x10000
	s_cmp_eq_u32 vcc_lo, 12
	s_cselect_b32 s75, s15, s73
	s_cselect_b32 s74, s78, s72
	v_add_u32_e32 v150, s76, v80
	s_cselect_b32 s73, s11, s97
	s_cselect_b32 s72, s79, s96
	s_add_i32 vcc_hi, 16, 0x14000
	ds_read_b128 v[142:145], v150
	ds_read_b128 v[146:149], v150 offset:1024
	ds_read_b128 v[160:163], v150 offset:2048
	ds_read_b128 v[166:169], v150 offset:3072
	v_add_u32_e32 v150, vcc_hi, v80
	ds_read_b128 v[170:173], v150
	ds_read_b128 v[174:177], v150 offset:1024
	ds_read_b128 v[178:181], v150 offset:2048
	ds_read_b128 v[182:185], v150 offset:3072
	v_lshl_add_u64 v[150:151], s[60:61], 0, v[138:139]
	s_add_i32 m0, s13, 0xc000
	ds_read_b128 v[186:189], v164
	ds_read_b128 v[204:207], v164 offset:1024
	ds_read_b128 v[214:217], v164 offset:2048
	ds_read_b128 v[218:221], v164 offset:3072
	ds_read_b128 v[222:225], v164 offset:4096
	ds_read_b128 v[226:229], v164 offset:5120
	ds_read_b128 v[230:233], v164 offset:6144
	ds_read_b128 v[234:237], v164 offset:7168
	global_load_lds_dwordx4 v[150:151], off
	v_lshl_add_u64 v[150:151], s[60:61], 0, v[140:141]
	s_add_i32 m0, s13, 0xe000
	s_nop 0
	global_load_lds_dwordx4 v[150:151], off
	s_waitcnt vmcnt(8)
	s_waitcnt lgkmcnt(0)
	s_barrier
	s_waitcnt lgkmcnt(0)
	v_mfma_f32_16x16x32_bf16 v[126:129], v[142:145], v[186:189], v[126:129]
	v_mfma_f32_16x16x32_bf16 v[122:125], v[160:163], v[186:189], v[122:125]
	v_mfma_f32_16x16x32_bf16 v[110:113], v[142:145], v[214:217], v[110:113]
	v_mfma_f32_16x16x32_bf16 v[106:109], v[160:163], v[214:217], v[106:109]
	v_mfma_f32_16x16x32_bf16 v[94:97], v[142:145], v[222:225], v[94:97]
	v_mfma_f32_16x16x32_bf16 v[90:93], v[160:163], v[222:225], v[90:93]
	v_mfma_f32_16x16x32_bf16 v[76:79], v[142:145], v[230:233], v[76:79]
	v_mfma_f32_16x16x32_bf16 v[72:75], v[160:163], v[230:233], v[72:75]
	v_mfma_f32_16x16x32_bf16 v[126:129], v[146:149], v[204:207], v[126:129]
	v_mfma_f32_16x16x32_bf16 v[122:125], v[166:169], v[204:207], v[122:125]
	v_mfma_f32_16x16x32_bf16 v[110:113], v[146:149], v[218:221], v[110:113]
	v_mfma_f32_16x16x32_bf16 v[106:109], v[166:169], v[218:221], v[106:109]
	v_mfma_f32_16x16x32_bf16 v[94:97], v[146:149], v[226:229], v[94:97]
	v_mfma_f32_16x16x32_bf16 v[90:93], v[166:169], v[226:229], v[90:93]
	v_mfma_f32_16x16x32_bf16 v[76:79], v[146:149], v[234:237], v[76:79]
	v_mfma_f32_16x16x32_bf16 v[72:75], v[166:169], v[234:237], v[72:75]
	v_mfma_f32_16x16x32_bf16 v[118:121], v[170:173], v[186:189], v[118:121]
	v_mfma_f32_16x16x32_bf16 v[114:117], v[178:181], v[186:189], v[114:117]
	v_mfma_f32_16x16x32_bf16 v[102:105], v[170:173], v[214:217], v[102:105]
	v_mfma_f32_16x16x32_bf16 v[98:101], v[178:181], v[214:217], v[98:101]
	v_mfma_f32_16x16x32_bf16 v[86:89], v[170:173], v[222:225], v[86:89]
	v_mfma_f32_16x16x32_bf16 v[82:85], v[178:181], v[222:225], v[82:85]
	v_mfma_f32_16x16x32_bf16 v[68:71], v[170:173], v[230:233], v[68:71]
	v_mfma_f32_16x16x32_bf16 v[64:67], v[178:181], v[230:233], v[64:67]
	v_mfma_f32_16x16x32_bf16 v[118:121], v[174:177], v[204:207], v[118:121]
	v_mfma_f32_16x16x32_bf16 v[114:117], v[182:185], v[204:207], v[114:117]
	v_mfma_f32_16x16x32_bf16 v[102:105], v[174:177], v[218:221], v[102:105]
	v_mfma_f32_16x16x32_bf16 v[98:101], v[182:185], v[218:221], v[98:101]
	v_mfma_f32_16x16x32_bf16 v[86:89], v[174:177], v[226:229], v[86:89]
	v_mfma_f32_16x16x32_bf16 v[82:85], v[182:185], v[226:229], v[82:85]
	v_mfma_f32_16x16x32_bf16 v[68:71], v[174:177], v[234:237], v[68:71]
	v_mfma_f32_16x16x32_bf16 v[64:67], v[182:185], v[234:237], v[64:67]
	s_barrier
	s_add_i32 s76, s76, s4
	v_lshl_add_u64 v[150:151], s[72:73], 0, v[134:135]
	s_mov_b32 m0, s76
	ds_read_b128 v[186:189], v164 offset:16384
	ds_read_b128 v[204:207], v164 offset:17408
	ds_read_b128 v[214:217], v164 offset:18432
	ds_read_b128 v[218:221], v164 offset:19456
	ds_read_b128 v[222:225], v164 offset:20480
	ds_read_b128 v[226:229], v164 offset:21504
	ds_read_b128 v[230:233], v164 offset:22528
	ds_read_b128 v[234:237], v164 offset:23552
	global_load_lds_dwordx4 v[150:151], off
	s_add_i32 m0, s76, 0x2000
	s_add_u32 s76, s72, 0x40000
	v_lshl_add_u64 v[190:191], s[72:73], 0, v[130:131]
	s_addc_u32 s77, s73, 0
	s_add_i32 vcc_hi, vcc_hi, s4
	global_load_lds_dwordx4 v[190:191], off
	v_lshl_add_u64 v[208:209], s[76:77], 0, v[134:135]
	s_mov_b32 m0, vcc_hi
	v_lshl_add_u64 v[238:239], s[74:75], 0, v[132:133]
	global_load_lds_dwordx4 v[208:209], off
	v_lshl_add_u64 v[208:209], s[76:77], 0, v[130:131]
	s_add_i32 m0, vcc_hi, 0x2000
	s_nop 0
	global_load_lds_dwordx4 v[208:209], off
	v_lshl_add_u64 v[208:209], s[74:75], 0, v[136:137]
	s_mov_b32 m0, s13
	s_nop 0
	global_load_lds_dwordx4 v[208:209], off
	s_mov_b32 m0, s25
	s_nop 0
	global_load_lds_dwordx4 v[238:239], off
	s_waitcnt vmcnt(8)
	s_waitcnt lgkmcnt(0)
	s_barrier
	s_waitcnt lgkmcnt(0)
	v_mfma_f32_16x16x32_bf16 v[60:63], v[142:145], v[186:189], v[60:63]
	v_mfma_f32_16x16x32_bf16 v[56:59], v[160:163], v[186:189], v[56:59]
	v_mfma_f32_16x16x32_bf16 v[44:47], v[142:145], v[214:217], v[44:47]
	v_mfma_f32_16x16x32_bf16 v[40:43], v[160:163], v[214:217], v[40:43]
	v_mfma_f32_16x16x32_bf16 v[28:31], v[142:145], v[222:225], v[28:31]
	v_mfma_f32_16x16x32_bf16 v[24:27], v[160:163], v[222:225], v[24:27]
	v_mfma_f32_16x16x32_bf16 v[12:15], v[142:145], v[230:233], v[12:15]
	v_mfma_f32_16x16x32_bf16 v[8:11], v[160:163], v[230:233], v[8:11]
	v_mfma_f32_16x16x32_bf16 v[60:63], v[146:149], v[204:207], v[60:63]
	v_mfma_f32_16x16x32_bf16 v[56:59], v[166:169], v[204:207], v[56:59]
	v_mfma_f32_16x16x32_bf16 v[44:47], v[146:149], v[218:221], v[44:47]
	v_mfma_f32_16x16x32_bf16 v[40:43], v[166:169], v[218:221], v[40:43]
	v_mfma_f32_16x16x32_bf16 v[28:31], v[146:149], v[226:229], v[28:31]
	v_mfma_f32_16x16x32_bf16 v[24:27], v[166:169], v[226:229], v[24:27]
	v_mfma_f32_16x16x32_bf16 v[12:15], v[146:149], v[234:237], v[12:15]
	v_mfma_f32_16x16x32_bf16 v[8:11], v[166:169], v[234:237], v[8:11]
	v_mfma_f32_16x16x32_bf16 v[52:55], v[170:173], v[186:189], v[52:55]
	v_mfma_f32_16x16x32_bf16 v[48:51], v[178:181], v[186:189], v[48:51]
	v_mfma_f32_16x16x32_bf16 v[36:39], v[170:173], v[214:217], v[36:39]
	v_mfma_f32_16x16x32_bf16 v[32:35], v[178:181], v[214:217], v[32:35]
	v_mfma_f32_16x16x32_bf16 v[20:23], v[170:173], v[222:225], v[20:23]
	v_mfma_f32_16x16x32_bf16 v[16:19], v[178:181], v[222:225], v[16:19]
	v_mfma_f32_16x16x32_bf16 v[4:7], v[170:173], v[230:233], v[4:7]
	v_mfma_f32_16x16x32_bf16 v[0:3], v[178:181], v[230:233], v[0:3]
	v_mfma_f32_16x16x32_bf16 v[52:55], v[174:177], v[204:207], v[52:55]
	v_mfma_f32_16x16x32_bf16 v[48:51], v[182:185], v[204:207], v[48:51]
	v_mfma_f32_16x16x32_bf16 v[36:39], v[174:177], v[218:221], v[36:39]
	v_mfma_f32_16x16x32_bf16 v[32:35], v[182:185], v[218:221], v[32:35]
	v_mfma_f32_16x16x32_bf16 v[20:23], v[174:177], v[226:229], v[20:23]
	v_mfma_f32_16x16x32_bf16 v[16:19], v[182:185], v[226:229], v[16:19]
	v_mfma_f32_16x16x32_bf16 v[4:7], v[174:177], v[234:237], v[4:7]
	v_mfma_f32_16x16x32_bf16 v[0:3], v[182:185], v[234:237], v[0:3]
	s_barrier
	s_add_i32 s76, 16, 0x18000
	v_add_u32_e32 v165, s76, v80
	s_add_i32 s77, 16, 0x1c000
	ds_read_b128 v[142:145], v165
	ds_read_b128 v[146:149], v165 offset:1024
	ds_read_b128 v[160:163], v165 offset:2048
	ds_read_b128 v[166:169], v165 offset:3072
	v_add_u32_e32 v165, s77, v80
	ds_read_b128 v[170:173], v165
	ds_read_b128 v[174:177], v165 offset:1024
	ds_read_b128 v[178:181], v165 offset:2048
	ds_read_b128 v[182:185], v165 offset:3072
	s_add_u32 s74, s74, 0x40000
	s_addc_u32 s75, s75, 0
	s_mov_b32 m0, s30
	v_lshl_add_u64 v[240:241], s[74:75], 0, v[136:137]
	ds_read_b128 v[186:189], v164 offset:32768
	ds_read_b128 v[204:207], v164 offset:33792
	ds_read_b128 v[214:217], v164 offset:34816
	ds_read_b128 v[218:221], v164 offset:35840
	ds_read_b128 v[222:225], v164 offset:36864
	ds_read_b128 v[226:229], v164 offset:37888
	ds_read_b128 v[230:233], v164 offset:38912
	ds_read_b128 v[234:237], v164 offset:39936
	global_load_lds_dwordx4 v[240:241], off
	v_lshl_add_u64 v[240:241], s[74:75], 0, v[132:133]
	s_mov_b32 m0, s33
	s_nop 0
	global_load_lds_dwordx4 v[240:241], off
	s_waitcnt vmcnt(8)
	s_waitcnt lgkmcnt(0)
	s_barrier
	s_waitcnt lgkmcnt(0)
	v_mfma_f32_16x16x32_bf16 v[126:129], v[142:145], v[186:189], v[126:129]
	v_mfma_f32_16x16x32_bf16 v[122:125], v[160:163], v[186:189], v[122:125]
	v_mfma_f32_16x16x32_bf16 v[110:113], v[142:145], v[214:217], v[110:113]
	v_mfma_f32_16x16x32_bf16 v[106:109], v[160:163], v[214:217], v[106:109]
	v_mfma_f32_16x16x32_bf16 v[94:97], v[142:145], v[222:225], v[94:97]
	v_mfma_f32_16x16x32_bf16 v[90:93], v[160:163], v[222:225], v[90:93]
	v_mfma_f32_16x16x32_bf16 v[76:79], v[142:145], v[230:233], v[76:79]
	v_mfma_f32_16x16x32_bf16 v[72:75], v[160:163], v[230:233], v[72:75]
	v_mfma_f32_16x16x32_bf16 v[126:129], v[146:149], v[204:207], v[126:129]
	v_mfma_f32_16x16x32_bf16 v[122:125], v[166:169], v[204:207], v[122:125]
	v_mfma_f32_16x16x32_bf16 v[110:113], v[146:149], v[218:221], v[110:113]
	v_mfma_f32_16x16x32_bf16 v[106:109], v[166:169], v[218:221], v[106:109]
	v_mfma_f32_16x16x32_bf16 v[94:97], v[146:149], v[226:229], v[94:97]
	v_mfma_f32_16x16x32_bf16 v[90:93], v[166:169], v[226:229], v[90:93]
	v_mfma_f32_16x16x32_bf16 v[76:79], v[146:149], v[234:237], v[76:79]
	v_mfma_f32_16x16x32_bf16 v[72:75], v[166:169], v[234:237], v[72:75]
	v_mfma_f32_16x16x32_bf16 v[118:121], v[170:173], v[186:189], v[118:121]
	v_mfma_f32_16x16x32_bf16 v[114:117], v[178:181], v[186:189], v[114:117]
	v_mfma_f32_16x16x32_bf16 v[102:105], v[170:173], v[214:217], v[102:105]
	v_mfma_f32_16x16x32_bf16 v[98:101], v[178:181], v[214:217], v[98:101]
	v_mfma_f32_16x16x32_bf16 v[86:89], v[170:173], v[222:225], v[86:89]
	v_mfma_f32_16x16x32_bf16 v[82:85], v[178:181], v[222:225], v[82:85]
	v_mfma_f32_16x16x32_bf16 v[68:71], v[170:173], v[230:233], v[68:71]
	v_mfma_f32_16x16x32_bf16 v[64:67], v[178:181], v[230:233], v[64:67]
	v_mfma_f32_16x16x32_bf16 v[118:121], v[174:177], v[204:207], v[118:121]
	v_mfma_f32_16x16x32_bf16 v[114:117], v[182:185], v[204:207], v[114:117]
	v_mfma_f32_16x16x32_bf16 v[102:105], v[174:177], v[218:221], v[102:105]
	v_mfma_f32_16x16x32_bf16 v[98:101], v[182:185], v[218:221], v[98:101]
	v_mfma_f32_16x16x32_bf16 v[86:89], v[174:177], v[226:229], v[86:89]
	v_mfma_f32_16x16x32_bf16 v[82:85], v[182:185], v[226:229], v[82:85]
	v_mfma_f32_16x16x32_bf16 v[68:71], v[174:177], v[234:237], v[68:71]
	v_mfma_f32_16x16x32_bf16 v[64:67], v[182:185], v[234:237], v[64:67]
	s_barrier
	s_add_i32 s74, s76, s4
	v_lshl_add_u64 v[150:151], v[150:151], 0, s[20:21]
	s_mov_b32 m0, s74
	ds_read_b128 v[186:189], v164 offset:49152
	ds_read_b128 v[204:207], v164 offset:50176
	ds_read_b128 v[214:217], v164 offset:51200
	ds_read_b128 v[218:221], v164 offset:52224
	ds_read_b128 v[222:225], v164 offset:53248
	ds_read_b128 v[226:229], v164 offset:54272
	ds_read_b128 v[230:233], v164 offset:55296
	ds_read_b128 v[234:237], v164 offset:56320
	global_load_lds_dwordx4 v[150:151], off
	s_add_i32 m0, s74, 0x2000
	s_add_u32 s72, s72, 0x40080
	v_lshl_add_u64 v[150:151], v[190:191], 0, s[20:21]
	s_addc_u32 s73, s73, 0
	s_add_i32 s74, s77, s4
	global_load_lds_dwordx4 v[150:151], off
	v_lshl_add_u64 v[150:151], s[72:73], 0, v[134:135]
	s_mov_b32 m0, s74
	s_nop 0
	global_load_lds_dwordx4 v[150:151], off
	v_lshl_add_u64 v[150:151], s[72:73], 0, v[130:131]
	s_add_i32 m0, s74, 0x2000
	s_nop 0
	global_load_lds_dwordx4 v[150:151], off
	v_lshl_add_u64 v[150:151], v[208:209], 0, s[20:21]
	s_mov_b32 m0, s34
	s_nop 0
	global_load_lds_dwordx4 v[150:151], off
	v_lshl_add_u64 v[150:151], v[238:239], 0, s[20:21]
	s_mov_b32 m0, s36
	s_nop 0
	global_load_lds_dwordx4 v[150:151], off
	s_waitcnt vmcnt(8)
	s_waitcnt lgkmcnt(0)
	s_barrier
	s_waitcnt lgkmcnt(0)
	v_mfma_f32_16x16x32_bf16 v[60:63], v[142:145], v[186:189], v[60:63]
	v_mfma_f32_16x16x32_bf16 v[56:59], v[160:163], v[186:189], v[56:59]
	v_mfma_f32_16x16x32_bf16 v[44:47], v[142:145], v[214:217], v[44:47]
	v_mfma_f32_16x16x32_bf16 v[40:43], v[160:163], v[214:217], v[40:43]
	v_mfma_f32_16x16x32_bf16 v[28:31], v[142:145], v[222:225], v[28:31]
	v_mfma_f32_16x16x32_bf16 v[24:27], v[160:163], v[222:225], v[24:27]
	v_mfma_f32_16x16x32_bf16 v[12:15], v[142:145], v[230:233], v[12:15]
	v_mfma_f32_16x16x32_bf16 v[8:11], v[160:163], v[230:233], v[8:11]
	v_mfma_f32_16x16x32_bf16 v[60:63], v[146:149], v[204:207], v[60:63]
	v_mfma_f32_16x16x32_bf16 v[56:59], v[166:169], v[204:207], v[56:59]
	v_mfma_f32_16x16x32_bf16 v[44:47], v[146:149], v[218:221], v[44:47]
	v_mfma_f32_16x16x32_bf16 v[40:43], v[166:169], v[218:221], v[40:43]
	v_mfma_f32_16x16x32_bf16 v[28:31], v[146:149], v[226:229], v[28:31]
	v_mfma_f32_16x16x32_bf16 v[24:27], v[166:169], v[226:229], v[24:27]
	v_mfma_f32_16x16x32_bf16 v[12:15], v[146:149], v[234:237], v[12:15]
	v_mfma_f32_16x16x32_bf16 v[8:11], v[166:169], v[234:237], v[8:11]
	v_mfma_f32_16x16x32_bf16 v[52:55], v[170:173], v[186:189], v[52:55]
	v_mfma_f32_16x16x32_bf16 v[48:51], v[178:181], v[186:189], v[48:51]
	v_mfma_f32_16x16x32_bf16 v[36:39], v[170:173], v[214:217], v[36:39]
	v_mfma_f32_16x16x32_bf16 v[32:35], v[178:181], v[214:217], v[32:35]
	v_mfma_f32_16x16x32_bf16 v[20:23], v[170:173], v[222:225], v[20:23]
	v_mfma_f32_16x16x32_bf16 v[16:19], v[178:181], v[222:225], v[16:19]
	v_mfma_f32_16x16x32_bf16 v[4:7], v[170:173], v[230:233], v[4:7]
	v_mfma_f32_16x16x32_bf16 v[0:3], v[178:181], v[230:233], v[0:3]
	v_mfma_f32_16x16x32_bf16 v[52:55], v[174:177], v[204:207], v[52:55]
	v_mfma_f32_16x16x32_bf16 v[48:51], v[182:185], v[204:207], v[48:51]
	v_mfma_f32_16x16x32_bf16 v[36:39], v[174:177], v[218:221], v[36:39]
	v_mfma_f32_16x16x32_bf16 v[32:35], v[182:185], v[218:221], v[32:35]
	v_mfma_f32_16x16x32_bf16 v[20:23], v[174:177], v[226:229], v[20:23]
	v_mfma_f32_16x16x32_bf16 v[16:19], v[182:185], v[226:229], v[16:19]
	v_mfma_f32_16x16x32_bf16 v[4:7], v[174:177], v[234:237], v[4:7]
	v_mfma_f32_16x16x32_bf16 v[0:3], v[182:185], v[234:237], v[0:3]
	s_barrier
	s_add_i32 vcc_lo, vcc_lo, 2
	s_add_u32 s60, s60, 0x100
	s_addc_u32 s61, s61, 0
	s_add_u32 s96, s96, 0x100
	s_addc_u32 s97, s97, 0
	s_cmp_gt_u32 vcc_lo, 13
	s_cbranch_scc0 .LBB0_167
	s_and_b64 vcc, exec, s[6:7]
	s_cbranch_vccz .LBB0_170
	s_barrier

.LBB0_193:
	s_add_u32 s44, s40, 0x100
	s_addc_u32 s45, s41, 0
	s_add_i32 s76, 16, 0x10000
	s_cmp_eq_u32 s78, 40
	s_cselect_b32 s61, s11, s45
	s_cselect_b32 s60, s10, s44
	v_add_u32_e32 v80, s76, v144
	s_cselect_b32 s55, s15, s75
	s_cselect_b32 s54, s14, s74
	s_add_i32 s77, 16, 0x14000
	ds_read_b128 v[146:149], v80
	ds_read_b128 v[160:163], v80 offset:1024
	ds_read_b128 v[164:167], v80 offset:2048
	ds_read_b128 v[168:171], v80 offset:3072
	v_add_u32_e32 v80, s77, v144
	ds_read_b128 v[172:175], v80
	ds_read_b128 v[176:179], v80 offset:1024
	ds_read_b128 v[180:183], v80 offset:2048
	ds_read_b128 v[184:187], v80 offset:3072
	v_lshl_add_u64 v[142:143], s[40:41], 0, v[138:139]
	s_add_i32 m0, s13, 0xc000
	ds_read_b128 v[188:191], v145
	ds_read_b128 v[204:207], v145 offset:1024
	ds_read_b128 v[214:217], v145 offset:2048
	ds_read_b128 v[218:221], v145 offset:3072
	ds_read_b128 v[222:225], v145 offset:4096
	ds_read_b128 v[226:229], v145 offset:5120
	ds_read_b128 v[230:233], v145 offset:6144
	ds_read_b128 v[234:237], v145 offset:7168
	global_load_lds_dwordx4 v[142:143], off
	v_lshl_add_u64 v[142:143], s[40:41], 0, v[140:141]
	s_add_i32 m0, s13, 0xe000
	s_nop 0
	global_load_lds_dwordx4 v[142:143], off
	s_waitcnt vmcnt(8)
	s_waitcnt lgkmcnt(0)
	s_barrier
	s_waitcnt lgkmcnt(0)
	v_mfma_f32_16x16x32_bf16 v[126:129], v[146:149], v[188:191], v[126:129]
	v_mfma_f32_16x16x32_bf16 v[122:125], v[164:167], v[188:191], v[122:125]
	v_mfma_f32_16x16x32_bf16 v[110:113], v[146:149], v[214:217], v[110:113]
	v_mfma_f32_16x16x32_bf16 v[106:109], v[164:167], v[214:217], v[106:109]
	v_mfma_f32_16x16x32_bf16 v[94:97], v[146:149], v[222:225], v[94:97]
	v_mfma_f32_16x16x32_bf16 v[90:93], v[164:167], v[222:225], v[90:93]
	v_mfma_f32_16x16x32_bf16 v[76:79], v[146:149], v[230:233], v[76:79]
	v_mfma_f32_16x16x32_bf16 v[72:75], v[164:167], v[230:233], v[72:75]
	v_mfma_f32_16x16x32_bf16 v[126:129], v[160:163], v[204:207], v[126:129]
	v_mfma_f32_16x16x32_bf16 v[122:125], v[168:171], v[204:207], v[122:125]
	v_mfma_f32_16x16x32_bf16 v[110:113], v[160:163], v[218:221], v[110:113]
	v_mfma_f32_16x16x32_bf16 v[106:109], v[168:171], v[218:221], v[106:109]
	v_mfma_f32_16x16x32_bf16 v[94:97], v[160:163], v[226:229], v[94:97]
	v_mfma_f32_16x16x32_bf16 v[90:93], v[168:171], v[226:229], v[90:93]
	v_mfma_f32_16x16x32_bf16 v[76:79], v[160:163], v[234:237], v[76:79]
	v_mfma_f32_16x16x32_bf16 v[72:75], v[168:171], v[234:237], v[72:75]
	v_mfma_f32_16x16x32_bf16 v[118:121], v[172:175], v[188:191], v[118:121]
	v_mfma_f32_16x16x32_bf16 v[114:117], v[180:183], v[188:191], v[114:117]
	v_mfma_f32_16x16x32_bf16 v[102:105], v[172:175], v[214:217], v[102:105]
	v_mfma_f32_16x16x32_bf16 v[98:101], v[180:183], v[214:217], v[98:101]
	v_mfma_f32_16x16x32_bf16 v[86:89], v[172:175], v[222:225], v[86:89]
	v_mfma_f32_16x16x32_bf16 v[82:85], v[180:183], v[222:225], v[82:85]
	v_mfma_f32_16x16x32_bf16 v[68:71], v[172:175], v[230:233], v[68:71]
	v_mfma_f32_16x16x32_bf16 v[64:67], v[180:183], v[230:233], v[64:67]
	v_mfma_f32_16x16x32_bf16 v[118:121], v[176:179], v[204:207], v[118:121]
	v_mfma_f32_16x16x32_bf16 v[114:117], v[184:187], v[204:207], v[114:117]
	v_mfma_f32_16x16x32_bf16 v[102:105], v[176:179], v[218:221], v[102:105]
	v_mfma_f32_16x16x32_bf16 v[98:101], v[184:187], v[218:221], v[98:101]
	v_mfma_f32_16x16x32_bf16 v[86:89], v[176:179], v[226:229], v[86:89]
	v_mfma_f32_16x16x32_bf16 v[82:85], v[184:187], v[226:229], v[82:85]
	v_mfma_f32_16x16x32_bf16 v[68:71], v[176:179], v[234:237], v[68:71]
	v_mfma_f32_16x16x32_bf16 v[64:67], v[184:187], v[234:237], v[64:67]
	s_barrier
	s_add_i32 s40, s76, s4
	v_lshl_add_u64 v[142:143], s[54:55], 0, v[134:135]
	s_mov_b32 m0, s40
	ds_read_b128 v[188:191], v145 offset:16384
	ds_read_b128 v[204:207], v145 offset:17408
	ds_read_b128 v[214:217], v145 offset:18432
	ds_read_b128 v[218:221], v145 offset:19456
	ds_read_b128 v[222:225], v145 offset:20480
	ds_read_b128 v[226:229], v145 offset:21504
	ds_read_b128 v[230:233], v145 offset:22528
	ds_read_b128 v[234:237], v145 offset:23552
	global_load_lds_dwordx4 v[142:143], off
	s_add_i32 m0, s40, 0x2000
	s_add_u32 s40, s54, 0xb0000
	v_lshl_add_u64 v[150:151], s[54:55], 0, v[130:131]
	s_addc_u32 s41, s55, 0
	s_add_i32 s76, s77, s4
	global_load_lds_dwordx4 v[150:151], off
	v_lshl_add_u64 v[208:209], s[40:41], 0, v[134:135]
	s_mov_b32 m0, s76
	v_lshl_add_u64 v[238:239], s[60:61], 0, v[132:133]
	global_load_lds_dwordx4 v[208:209], off
	v_lshl_add_u64 v[208:209], s[40:41], 0, v[130:131]
	s_add_i32 m0, s76, 0x2000
	s_nop 0
	global_load_lds_dwordx4 v[208:209], off
	v_lshl_add_u64 v[208:209], s[60:61], 0, v[136:137]
	s_mov_b32 m0, s13
	s_nop 0
	global_load_lds_dwordx4 v[208:209], off
	s_mov_b32 m0, s25
	s_nop 0
	global_load_lds_dwordx4 v[238:239], off
	s_waitcnt vmcnt(8)
	s_waitcnt lgkmcnt(0)
	s_barrier
	s_waitcnt lgkmcnt(0)
	v_mfma_f32_16x16x32_bf16 v[60:63], v[146:149], v[188:191], v[60:63]
	v_mfma_f32_16x16x32_bf16 v[56:59], v[164:167], v[188:191], v[56:59]
	v_mfma_f32_16x16x32_bf16 v[44:47], v[146:149], v[214:217], v[44:47]
	v_mfma_f32_16x16x32_bf16 v[40:43], v[164:167], v[214:217], v[40:43]
	v_mfma_f32_16x16x32_bf16 v[28:31], v[146:149], v[222:225], v[28:31]
	v_mfma_f32_16x16x32_bf16 v[24:27], v[164:167], v[222:225], v[24:27]
	v_mfma_f32_16x16x32_bf16 v[12:15], v[146:149], v[230:233], v[12:15]
	v_mfma_f32_16x16x32_bf16 v[8:11], v[164:167], v[230:233], v[8:11]
	v_mfma_f32_16x16x32_bf16 v[60:63], v[160:163], v[204:207], v[60:63]
	v_mfma_f32_16x16x32_bf16 v[56:59], v[168:171], v[204:207], v[56:59]
	v_mfma_f32_16x16x32_bf16 v[44:47], v[160:163], v[218:221], v[44:47]
	v_mfma_f32_16x16x32_bf16 v[40:43], v[168:171], v[218:221], v[40:43]
	v_mfma_f32_16x16x32_bf16 v[28:31], v[160:163], v[226:229], v[28:31]
	v_mfma_f32_16x16x32_bf16 v[24:27], v[168:171], v[226:229], v[24:27]
	v_mfma_f32_16x16x32_bf16 v[12:15], v[160:163], v[234:237], v[12:15]
	v_mfma_f32_16x16x32_bf16 v[8:11], v[168:171], v[234:237], v[8:11]
	v_mfma_f32_16x16x32_bf16 v[52:55], v[172:175], v[188:191], v[52:55]
	v_mfma_f32_16x16x32_bf16 v[48:51], v[180:183], v[188:191], v[48:51]
	v_mfma_f32_16x16x32_bf16 v[36:39], v[172:175], v[214:217], v[36:39]
	v_mfma_f32_16x16x32_bf16 v[32:35], v[180:183], v[214:217], v[32:35]
	v_mfma_f32_16x16x32_bf16 v[20:23], v[172:175], v[222:225], v[20:23]
	v_mfma_f32_16x16x32_bf16 v[16:19], v[180:183], v[222:225], v[16:19]
	v_mfma_f32_16x16x32_bf16 v[4:7], v[172:175], v[230:233], v[4:7]
	v_mfma_f32_16x16x32_bf16 v[0:3], v[180:183], v[230:233], v[0:3]
	v_mfma_f32_16x16x32_bf16 v[52:55], v[176:179], v[204:207], v[52:55]
	v_mfma_f32_16x16x32_bf16 v[48:51], v[184:187], v[204:207], v[48:51]
	v_mfma_f32_16x16x32_bf16 v[36:39], v[176:179], v[218:221], v[36:39]
	v_mfma_f32_16x16x32_bf16 v[32:35], v[184:187], v[218:221], v[32:35]
	v_mfma_f32_16x16x32_bf16 v[20:23], v[176:179], v[226:229], v[20:23]
	v_mfma_f32_16x16x32_bf16 v[16:19], v[184:187], v[226:229], v[16:19]
	v_mfma_f32_16x16x32_bf16 v[4:7], v[176:179], v[234:237], v[4:7]
	v_mfma_f32_16x16x32_bf16 v[0:3], v[184:187], v[234:237], v[0:3]
	s_barrier
	s_add_i32 s76, 16, 0x18000
	v_add_u32_e32 v80, s76, v144
	s_add_i32 s77, 16, 0x1c000
	ds_read_b128 v[146:149], v80
	ds_read_b128 v[160:163], v80 offset:1024
	ds_read_b128 v[164:167], v80 offset:2048
	ds_read_b128 v[168:171], v80 offset:3072
	v_add_u32_e32 v80, s77, v144
	ds_read_b128 v[172:175], v80
	ds_read_b128 v[176:179], v80 offset:1024
	ds_read_b128 v[180:183], v80 offset:2048
	ds_read_b128 v[184:187], v80 offset:3072
	s_add_u32 s40, s60, 0xb0000
	s_addc_u32 s41, s61, 0
	s_mov_b32 m0, s30
	v_lshl_add_u64 v[240:241], s[40:41], 0, v[136:137]
	ds_read_b128 v[188:191], v145 offset:32768
	ds_read_b128 v[204:207], v145 offset:33792
	ds_read_b128 v[214:217], v145 offset:34816
	ds_read_b128 v[218:221], v145 offset:35840
	ds_read_b128 v[222:225], v145 offset:36864
	ds_read_b128 v[226:229], v145 offset:37888
	ds_read_b128 v[230:233], v145 offset:38912
	ds_read_b128 v[234:237], v145 offset:39936
	global_load_lds_dwordx4 v[240:241], off
	v_lshl_add_u64 v[240:241], s[40:41], 0, v[132:133]
	s_mov_b32 m0, s33
	s_nop 0
	global_load_lds_dwordx4 v[240:241], off
	s_waitcnt vmcnt(8)
	s_waitcnt lgkmcnt(0)
	s_barrier
	s_waitcnt lgkmcnt(0)
	v_mfma_f32_16x16x32_bf16 v[126:129], v[146:149], v[188:191], v[126:129]
	v_mfma_f32_16x16x32_bf16 v[122:125], v[164:167], v[188:191], v[122:125]
	v_mfma_f32_16x16x32_bf16 v[110:113], v[146:149], v[214:217], v[110:113]
	v_mfma_f32_16x16x32_bf16 v[106:109], v[164:167], v[214:217], v[106:109]
	v_mfma_f32_16x16x32_bf16 v[94:97], v[146:149], v[222:225], v[94:97]
	v_mfma_f32_16x16x32_bf16 v[90:93], v[164:167], v[222:225], v[90:93]
	v_mfma_f32_16x16x32_bf16 v[76:79], v[146:149], v[230:233], v[76:79]
	v_mfma_f32_16x16x32_bf16 v[72:75], v[164:167], v[230:233], v[72:75]
	v_mfma_f32_16x16x32_bf16 v[126:129], v[160:163], v[204:207], v[126:129]
	v_mfma_f32_16x16x32_bf16 v[122:125], v[168:171], v[204:207], v[122:125]
	v_mfma_f32_16x16x32_bf16 v[110:113], v[160:163], v[218:221], v[110:113]
	v_mfma_f32_16x16x32_bf16 v[106:109], v[168:171], v[218:221], v[106:109]
	v_mfma_f32_16x16x32_bf16 v[94:97], v[160:163], v[226:229], v[94:97]
	v_mfma_f32_16x16x32_bf16 v[90:93], v[168:171], v[226:229], v[90:93]
	v_mfma_f32_16x16x32_bf16 v[76:79], v[160:163], v[234:237], v[76:79]
	v_mfma_f32_16x16x32_bf16 v[72:75], v[168:171], v[234:237], v[72:75]
	v_mfma_f32_16x16x32_bf16 v[118:121], v[172:175], v[188:191], v[118:121]
	v_mfma_f32_16x16x32_bf16 v[114:117], v[180:183], v[188:191], v[114:117]
	v_mfma_f32_16x16x32_bf16 v[102:105], v[172:175], v[214:217], v[102:105]
	v_mfma_f32_16x16x32_bf16 v[98:101], v[180:183], v[214:217], v[98:101]
	v_mfma_f32_16x16x32_bf16 v[86:89], v[172:175], v[222:225], v[86:89]
	v_mfma_f32_16x16x32_bf16 v[82:85], v[180:183], v[222:225], v[82:85]
	v_mfma_f32_16x16x32_bf16 v[68:71], v[172:175], v[230:233], v[68:71]
	v_mfma_f32_16x16x32_bf16 v[64:67], v[180:183], v[230:233], v[64:67]
	v_mfma_f32_16x16x32_bf16 v[118:121], v[176:179], v[204:207], v[118:121]
	v_mfma_f32_16x16x32_bf16 v[114:117], v[184:187], v[204:207], v[114:117]
	v_mfma_f32_16x16x32_bf16 v[102:105], v[176:179], v[218:221], v[102:105]
	v_mfma_f32_16x16x32_bf16 v[98:101], v[184:187], v[218:221], v[98:101]
	v_mfma_f32_16x16x32_bf16 v[86:89], v[176:179], v[226:229], v[86:89]
	v_mfma_f32_16x16x32_bf16 v[82:85], v[184:187], v[226:229], v[82:85]
	v_mfma_f32_16x16x32_bf16 v[68:71], v[176:179], v[234:237], v[68:71]
	v_mfma_f32_16x16x32_bf16 v[64:67], v[184:187], v[234:237], v[64:67]
	s_barrier
	s_add_i32 s40, s76, s4
	v_lshl_add_u64 v[142:143], v[142:143], 0, s[20:21]
	s_mov_b32 m0, s40
	ds_read_b128 v[188:191], v145 offset:49152
	ds_read_b128 v[204:207], v145 offset:50176
	ds_read_b128 v[214:217], v145 offset:51200
	ds_read_b128 v[218:221], v145 offset:52224
	ds_read_b128 v[222:225], v145 offset:53248
	ds_read_b128 v[226:229], v145 offset:54272
	ds_read_b128 v[230:233], v145 offset:55296
	ds_read_b128 v[234:237], v145 offset:56320
	global_load_lds_dwordx4 v[142:143], off
	s_add_i32 m0, s40, 0x2000
	s_add_u32 s40, s54, 0xb0080
	v_lshl_add_u64 v[142:143], v[150:151], 0, s[20:21]
	s_addc_u32 s41, s55, 0
	s_add_i32 s54, s77, s4
	global_load_lds_dwordx4 v[142:143], off
	v_lshl_add_u64 v[142:143], s[40:41], 0, v[134:135]
	s_mov_b32 m0, s54
	s_nop 0
	global_load_lds_dwordx4 v[142:143], off
	v_lshl_add_u64 v[142:143], s[40:41], 0, v[130:131]
	s_add_i32 m0, s54, 0x2000
	s_nop 0
	global_load_lds_dwordx4 v[142:143], off
	v_lshl_add_u64 v[142:143], v[208:209], 0, s[20:21]
	s_mov_b32 m0, s34
	s_nop 0
	global_load_lds_dwordx4 v[142:143], off
	v_lshl_add_u64 v[142:143], v[238:239], 0, s[20:21]
	s_mov_b32 m0, s36
	s_nop 0
	global_load_lds_dwordx4 v[142:143], off
	s_waitcnt vmcnt(8)
	s_waitcnt lgkmcnt(0)
	s_barrier
	s_waitcnt lgkmcnt(0)
	v_mfma_f32_16x16x32_bf16 v[60:63], v[146:149], v[188:191], v[60:63]
	v_mfma_f32_16x16x32_bf16 v[56:59], v[164:167], v[188:191], v[56:59]
	v_mfma_f32_16x16x32_bf16 v[44:47], v[146:149], v[214:217], v[44:47]
	v_mfma_f32_16x16x32_bf16 v[40:43], v[164:167], v[214:217], v[40:43]
	v_mfma_f32_16x16x32_bf16 v[28:31], v[146:149], v[222:225], v[28:31]
	v_mfma_f32_16x16x32_bf16 v[24:27], v[164:167], v[222:225], v[24:27]
	v_mfma_f32_16x16x32_bf16 v[12:15], v[146:149], v[230:233], v[12:15]
	v_mfma_f32_16x16x32_bf16 v[8:11], v[164:167], v[230:233], v[8:11]
	v_mfma_f32_16x16x32_bf16 v[60:63], v[160:163], v[204:207], v[60:63]
	v_mfma_f32_16x16x32_bf16 v[56:59], v[168:171], v[204:207], v[56:59]
	v_mfma_f32_16x16x32_bf16 v[44:47], v[160:163], v[218:221], v[44:47]
	v_mfma_f32_16x16x32_bf16 v[40:43], v[168:171], v[218:221], v[40:43]
	v_mfma_f32_16x16x32_bf16 v[28:31], v[160:163], v[226:229], v[28:31]
	v_mfma_f32_16x16x32_bf16 v[24:27], v[168:171], v[226:229], v[24:27]
	v_mfma_f32_16x16x32_bf16 v[12:15], v[160:163], v[234:237], v[12:15]
	v_mfma_f32_16x16x32_bf16 v[8:11], v[168:171], v[234:237], v[8:11]
	v_mfma_f32_16x16x32_bf16 v[52:55], v[172:175], v[188:191], v[52:55]
	v_mfma_f32_16x16x32_bf16 v[48:51], v[180:183], v[188:191], v[48:51]
	v_mfma_f32_16x16x32_bf16 v[36:39], v[172:175], v[214:217], v[36:39]
	v_mfma_f32_16x16x32_bf16 v[32:35], v[180:183], v[214:217], v[32:35]
	v_mfma_f32_16x16x32_bf16 v[20:23], v[172:175], v[222:225], v[20:23]
	v_mfma_f32_16x16x32_bf16 v[16:19], v[180:183], v[222:225], v[16:19]
	v_mfma_f32_16x16x32_bf16 v[4:7], v[172:175], v[230:233], v[4:7]
	v_mfma_f32_16x16x32_bf16 v[0:3], v[180:183], v[230:233], v[0:3]
	v_mfma_f32_16x16x32_bf16 v[52:55], v[176:179], v[204:207], v[52:55]
	v_mfma_f32_16x16x32_bf16 v[48:51], v[184:187], v[204:207], v[48:51]
	v_mfma_f32_16x16x32_bf16 v[36:39], v[176:179], v[218:221], v[36:39]
	v_mfma_f32_16x16x32_bf16 v[32:35], v[184:187], v[218:221], v[32:35]
	v_mfma_f32_16x16x32_bf16 v[20:23], v[176:179], v[226:229], v[20:23]
	v_mfma_f32_16x16x32_bf16 v[16:19], v[184:187], v[226:229], v[16:19]
	v_mfma_f32_16x16x32_bf16 v[4:7], v[176:179], v[234:237], v[4:7]
	v_mfma_f32_16x16x32_bf16 v[0:3], v[184:187], v[234:237], v[0:3]
	s_barrier
	s_add_i32 s78, s78, 2
	s_add_u32 s74, s74, 0x100
	s_addc_u32 s75, s75, 0
	s_cmp_gt_u32 s78, 41
	s_mov_b64 s[40:41], s[44:45]
	s_cbranch_scc0 .LBB0_193
	s_and_b64 vcc, exec, s[6:7]
	s_cbranch_vccz .LBB0_196
	s_barrier

.LBB0_227:
	s_add_u32 s54, s46, 0xfffc0080
	s_addc_u32 s55, s47, -1
	s_add_i32 s76, 16, 0x10000
	s_cmp_eq_u32 s78, 12
	s_cselect_b32 s61, s15, s55
	s_cselect_b32 s60, s72, s54
	v_add_u32_e32 v80, s76, v146
	s_cselect_b32 s55, s11, s75
	s_cselect_b32 s54, s73, s74
	s_add_i32 s77, 16, 0x14000
	ds_read_b128 v[142:145], v80
	ds_read_b128 v[148:151], v80 offset:1024
	ds_read_b128 v[160:163], v80 offset:2048
	ds_read_b128 v[164:167], v80 offset:3072
	v_add_u32_e32 v80, s77, v146
	ds_read_b128 v[168:171], v80
	ds_read_b128 v[172:175], v80 offset:1024
	ds_read_b128 v[176:179], v80 offset:2048
	ds_read_b128 v[180:183], v80 offset:3072
	v_lshl_add_u64 v[208:209], s[46:47], 0, v[138:139]
	s_add_i32 m0, s13, 0xc000
	ds_read_b128 v[184:187], v147
	ds_read_b128 v[188:191], v147 offset:1024
	ds_read_b128 v[204:207], v147 offset:2048
	ds_read_b128 v[214:217], v147 offset:3072
	ds_read_b128 v[218:221], v147 offset:4096
	ds_read_b128 v[222:225], v147 offset:5120
	ds_read_b128 v[226:229], v147 offset:6144
	ds_read_b128 v[230:233], v147 offset:7168
	global_load_lds_dwordx4 v[208:209], off
	v_lshl_add_u64 v[208:209], s[46:47], 0, v[140:141]
	s_add_i32 m0, s13, 0xe000
	s_nop 0
	global_load_lds_dwordx4 v[208:209], off
	s_waitcnt vmcnt(8)
	s_waitcnt lgkmcnt(0)
	s_barrier
	s_waitcnt lgkmcnt(0)
	v_mfma_f32_16x16x32_bf16 v[118:121], v[142:145], v[184:187], v[118:121]
	v_mfma_f32_16x16x32_bf16 v[114:117], v[160:163], v[184:187], v[114:117]
	v_mfma_f32_16x16x32_bf16 v[106:109], v[142:145], v[204:207], v[106:109]
	v_mfma_f32_16x16x32_bf16 v[98:101], v[160:163], v[204:207], v[98:101]
	v_mfma_f32_16x16x32_bf16 v[90:93], v[142:145], v[218:221], v[90:93]
	v_mfma_f32_16x16x32_bf16 v[82:85], v[160:163], v[218:221], v[82:85]
	v_mfma_f32_16x16x32_bf16 v[68:71], v[142:145], v[226:229], v[68:71]
	v_mfma_f32_16x16x32_bf16 v[64:67], v[160:163], v[226:229], v[64:67]
	v_mfma_f32_16x16x32_bf16 v[118:121], v[148:151], v[188:191], v[118:121]
	v_mfma_f32_16x16x32_bf16 v[114:117], v[164:167], v[188:191], v[114:117]
	v_mfma_f32_16x16x32_bf16 v[106:109], v[148:151], v[214:217], v[106:109]
	v_mfma_f32_16x16x32_bf16 v[98:101], v[164:167], v[214:217], v[98:101]
	v_mfma_f32_16x16x32_bf16 v[90:93], v[148:151], v[222:225], v[90:93]
	v_mfma_f32_16x16x32_bf16 v[82:85], v[164:167], v[222:225], v[82:85]
	v_mfma_f32_16x16x32_bf16 v[68:71], v[148:151], v[230:233], v[68:71]
	v_mfma_f32_16x16x32_bf16 v[64:67], v[164:167], v[230:233], v[64:67]
	v_mfma_f32_16x16x32_bf16 v[126:129], v[168:171], v[184:187], v[126:129]
	v_mfma_f32_16x16x32_bf16 v[122:125], v[176:179], v[184:187], v[122:125]
	v_mfma_f32_16x16x32_bf16 v[110:113], v[168:171], v[204:207], v[110:113]
	v_mfma_f32_16x16x32_bf16 v[102:105], v[176:179], v[204:207], v[102:105]
	v_mfma_f32_16x16x32_bf16 v[94:97], v[168:171], v[218:221], v[94:97]
	v_mfma_f32_16x16x32_bf16 v[86:89], v[176:179], v[218:221], v[86:89]
	v_mfma_f32_16x16x32_bf16 v[76:79], v[168:171], v[226:229], v[76:79]
	v_mfma_f32_16x16x32_bf16 v[72:75], v[176:179], v[226:229], v[72:75]
	v_mfma_f32_16x16x32_bf16 v[126:129], v[172:175], v[188:191], v[126:129]
	v_mfma_f32_16x16x32_bf16 v[122:125], v[180:183], v[188:191], v[122:125]
	v_mfma_f32_16x16x32_bf16 v[110:113], v[172:175], v[214:217], v[110:113]
	v_mfma_f32_16x16x32_bf16 v[102:105], v[180:183], v[214:217], v[102:105]
	v_mfma_f32_16x16x32_bf16 v[94:97], v[172:175], v[222:225], v[94:97]
	v_mfma_f32_16x16x32_bf16 v[86:89], v[180:183], v[222:225], v[86:89]
	v_mfma_f32_16x16x32_bf16 v[76:79], v[172:175], v[230:233], v[76:79]
	v_mfma_f32_16x16x32_bf16 v[72:75], v[180:183], v[230:233], v[72:75]
	s_barrier
	s_add_i32 s76, s76, s4
	v_lshl_add_u64 v[208:209], s[54:55], 0, v[134:135]
	s_mov_b32 m0, s76
	ds_read_b128 v[184:187], v147 offset:16384
	ds_read_b128 v[188:191], v147 offset:17408
	ds_read_b128 v[204:207], v147 offset:18432
	ds_read_b128 v[214:217], v147 offset:19456
	ds_read_b128 v[218:221], v147 offset:20480
	ds_read_b128 v[222:225], v147 offset:21504
	ds_read_b128 v[226:229], v147 offset:22528
	ds_read_b128 v[230:233], v147 offset:23552
	global_load_lds_dwordx4 v[208:209], off
	s_add_i32 m0, s76, 0x2000
	s_add_u32 s96, s54, 0x40000
	v_lshl_add_u64 v[234:235], s[54:55], 0, v[130:131]
	s_addc_u32 s97, s55, 0
	s_add_i32 s76, s77, s4
	global_load_lds_dwordx4 v[234:235], off
	v_lshl_add_u64 v[236:237], s[96:97], 0, v[134:135]
	s_mov_b32 m0, s76
	v_lshl_add_u64 v[238:239], s[60:61], 0, v[132:133]
	global_load_lds_dwordx4 v[236:237], off
	v_lshl_add_u64 v[236:237], s[96:97], 0, v[130:131]
	s_add_i32 m0, s76, 0x2000
	s_nop 0
	global_load_lds_dwordx4 v[236:237], off
	v_lshl_add_u64 v[236:237], s[60:61], 0, v[136:137]
	s_mov_b32 m0, s13
	s_nop 0
	global_load_lds_dwordx4 v[236:237], off
	s_mov_b32 m0, s25
	s_nop 0
	global_load_lds_dwordx4 v[238:239], off
	s_waitcnt vmcnt(8)
	s_waitcnt lgkmcnt(0)
	s_barrier
	s_waitcnt lgkmcnt(0)
	v_mfma_f32_16x16x32_bf16 v[52:55], v[142:145], v[184:187], v[52:55]
	v_mfma_f32_16x16x32_bf16 v[48:51], v[160:163], v[184:187], v[48:51]
	v_mfma_f32_16x16x32_bf16 v[36:39], v[142:145], v[204:207], v[36:39]
	v_mfma_f32_16x16x32_bf16 v[32:35], v[160:163], v[204:207], v[32:35]
	v_mfma_f32_16x16x32_bf16 v[20:23], v[142:145], v[218:221], v[20:23]
	v_mfma_f32_16x16x32_bf16 v[16:19], v[160:163], v[218:221], v[16:19]
	v_mfma_f32_16x16x32_bf16 v[8:11], v[142:145], v[226:229], v[8:11]
	v_mfma_f32_16x16x32_bf16 v[0:3], v[160:163], v[226:229], v[0:3]
	v_mfma_f32_16x16x32_bf16 v[52:55], v[148:151], v[188:191], v[52:55]
	v_mfma_f32_16x16x32_bf16 v[48:51], v[164:167], v[188:191], v[48:51]
	v_mfma_f32_16x16x32_bf16 v[36:39], v[148:151], v[214:217], v[36:39]
	v_mfma_f32_16x16x32_bf16 v[32:35], v[164:167], v[214:217], v[32:35]
	v_mfma_f32_16x16x32_bf16 v[20:23], v[148:151], v[222:225], v[20:23]
	v_mfma_f32_16x16x32_bf16 v[16:19], v[164:167], v[222:225], v[16:19]
	v_mfma_f32_16x16x32_bf16 v[8:11], v[148:151], v[230:233], v[8:11]
	v_mfma_f32_16x16x32_bf16 v[0:3], v[164:167], v[230:233], v[0:3]
	v_mfma_f32_16x16x32_bf16 v[60:63], v[168:171], v[184:187], v[60:63]
	v_mfma_f32_16x16x32_bf16 v[56:59], v[176:179], v[184:187], v[56:59]
	v_mfma_f32_16x16x32_bf16 v[44:47], v[168:171], v[204:207], v[44:47]
	v_mfma_f32_16x16x32_bf16 v[40:43], v[176:179], v[204:207], v[40:43]
	v_mfma_f32_16x16x32_bf16 v[28:31], v[168:171], v[218:221], v[28:31]
	v_mfma_f32_16x16x32_bf16 v[24:27], v[176:179], v[218:221], v[24:27]
	v_mfma_f32_16x16x32_bf16 v[12:15], v[168:171], v[226:229], v[12:15]
	v_mfma_f32_16x16x32_bf16 v[4:7], v[176:179], v[226:229], v[4:7]
	v_mfma_f32_16x16x32_bf16 v[60:63], v[172:175], v[188:191], v[60:63]
	v_mfma_f32_16x16x32_bf16 v[56:59], v[180:183], v[188:191], v[56:59]
	v_mfma_f32_16x16x32_bf16 v[44:47], v[172:175], v[214:217], v[44:47]
	v_mfma_f32_16x16x32_bf16 v[40:43], v[180:183], v[214:217], v[40:43]
	v_mfma_f32_16x16x32_bf16 v[28:31], v[172:175], v[222:225], v[28:31]
	v_mfma_f32_16x16x32_bf16 v[24:27], v[180:183], v[222:225], v[24:27]
	v_mfma_f32_16x16x32_bf16 v[12:15], v[172:175], v[230:233], v[12:15]
	v_mfma_f32_16x16x32_bf16 v[4:7], v[180:183], v[230:233], v[4:7]
	s_barrier
	s_add_i32 s76, 16, 0x18000
	v_add_u32_e32 v80, s76, v146
	s_add_i32 s77, 16, 0x1c000
	ds_read_b128 v[142:145], v80
	ds_read_b128 v[148:151], v80 offset:1024
	ds_read_b128 v[160:163], v80 offset:2048
	ds_read_b128 v[164:167], v80 offset:3072
	v_add_u32_e32 v80, s77, v146
	ds_read_b128 v[168:171], v80
	ds_read_b128 v[172:175], v80 offset:1024
	ds_read_b128 v[176:179], v80 offset:2048
	ds_read_b128 v[180:183], v80 offset:3072
	s_add_u32 s60, s60, 0x40000
	s_addc_u32 s61, s61, 0
	s_mov_b32 m0, s30
	v_lshl_add_u64 v[240:241], s[60:61], 0, v[136:137]
	ds_read_b128 v[184:187], v147 offset:32768
	ds_read_b128 v[188:191], v147 offset:33792
	ds_read_b128 v[204:207], v147 offset:34816
	ds_read_b128 v[214:217], v147 offset:35840
	ds_read_b128 v[218:221], v147 offset:36864
	ds_read_b128 v[222:225], v147 offset:37888
	ds_read_b128 v[226:229], v147 offset:38912
	ds_read_b128 v[230:233], v147 offset:39936
	global_load_lds_dwordx4 v[240:241], off
	v_lshl_add_u64 v[240:241], s[60:61], 0, v[132:133]
	s_mov_b32 m0, s33
	s_nop 0
	global_load_lds_dwordx4 v[240:241], off
	s_waitcnt vmcnt(8)
	s_waitcnt lgkmcnt(0)
	s_barrier
	s_waitcnt lgkmcnt(0)
	v_mfma_f32_16x16x32_bf16 v[118:121], v[142:145], v[184:187], v[118:121]
	v_mfma_f32_16x16x32_bf16 v[114:117], v[160:163], v[184:187], v[114:117]
	v_mfma_f32_16x16x32_bf16 v[106:109], v[142:145], v[204:207], v[106:109]
	v_mfma_f32_16x16x32_bf16 v[98:101], v[160:163], v[204:207], v[98:101]
	v_mfma_f32_16x16x32_bf16 v[90:93], v[142:145], v[218:221], v[90:93]
	v_mfma_f32_16x16x32_bf16 v[82:85], v[160:163], v[218:221], v[82:85]
	v_mfma_f32_16x16x32_bf16 v[68:71], v[142:145], v[226:229], v[68:71]
	v_mfma_f32_16x16x32_bf16 v[64:67], v[160:163], v[226:229], v[64:67]
	v_mfma_f32_16x16x32_bf16 v[118:121], v[148:151], v[188:191], v[118:121]
	v_mfma_f32_16x16x32_bf16 v[114:117], v[164:167], v[188:191], v[114:117]
	v_mfma_f32_16x16x32_bf16 v[106:109], v[148:151], v[214:217], v[106:109]
	v_mfma_f32_16x16x32_bf16 v[98:101], v[164:167], v[214:217], v[98:101]
	v_mfma_f32_16x16x32_bf16 v[90:93], v[148:151], v[222:225], v[90:93]
	v_mfma_f32_16x16x32_bf16 v[82:85], v[164:167], v[222:225], v[82:85]
	v_mfma_f32_16x16x32_bf16 v[68:71], v[148:151], v[230:233], v[68:71]
	v_mfma_f32_16x16x32_bf16 v[64:67], v[164:167], v[230:233], v[64:67]
	v_mfma_f32_16x16x32_bf16 v[126:129], v[168:171], v[184:187], v[126:129]
	v_mfma_f32_16x16x32_bf16 v[122:125], v[176:179], v[184:187], v[122:125]
	v_mfma_f32_16x16x32_bf16 v[110:113], v[168:171], v[204:207], v[110:113]
	v_mfma_f32_16x16x32_bf16 v[102:105], v[176:179], v[204:207], v[102:105]
	v_mfma_f32_16x16x32_bf16 v[94:97], v[168:171], v[218:221], v[94:97]
	v_mfma_f32_16x16x32_bf16 v[86:89], v[176:179], v[218:221], v[86:89]
	v_mfma_f32_16x16x32_bf16 v[76:79], v[168:171], v[226:229], v[76:79]
	v_mfma_f32_16x16x32_bf16 v[72:75], v[176:179], v[226:229], v[72:75]
	v_mfma_f32_16x16x32_bf16 v[126:129], v[172:175], v[188:191], v[126:129]
	v_mfma_f32_16x16x32_bf16 v[122:125], v[180:183], v[188:191], v[122:125]
	v_mfma_f32_16x16x32_bf16 v[110:113], v[172:175], v[214:217], v[110:113]
	v_mfma_f32_16x16x32_bf16 v[102:105], v[180:183], v[214:217], v[102:105]
	v_mfma_f32_16x16x32_bf16 v[94:97], v[172:175], v[222:225], v[94:97]
	v_mfma_f32_16x16x32_bf16 v[86:89], v[180:183], v[222:225], v[86:89]
	v_mfma_f32_16x16x32_bf16 v[76:79], v[172:175], v[230:233], v[76:79]
	v_mfma_f32_16x16x32_bf16 v[72:75], v[180:183], v[230:233], v[72:75]
	s_barrier
	s_add_i32 s60, s76, s4
	v_lshl_add_u64 v[208:209], v[208:209], 0, s[20:21]
	s_mov_b32 m0, s60
	ds_read_b128 v[184:187], v147 offset:49152
	ds_read_b128 v[188:191], v147 offset:50176
	ds_read_b128 v[204:207], v147 offset:51200
	ds_read_b128 v[214:217], v147 offset:52224
	ds_read_b128 v[218:221], v147 offset:53248
	ds_read_b128 v[222:225], v147 offset:54272
	ds_read_b128 v[226:229], v147 offset:55296
	ds_read_b128 v[230:233], v147 offset:56320
	global_load_lds_dwordx4 v[208:209], off
	s_add_i32 m0, s60, 0x2000
	s_add_u32 s54, s54, 0x40080
	v_lshl_add_u64 v[208:209], v[234:235], 0, s[20:21]
	s_addc_u32 s55, s55, 0
	s_add_i32 s60, s77, s4
	global_load_lds_dwordx4 v[208:209], off
	v_lshl_add_u64 v[208:209], s[54:55], 0, v[134:135]
	s_mov_b32 m0, s60
	s_nop 0
	global_load_lds_dwordx4 v[208:209], off
	v_lshl_add_u64 v[208:209], s[54:55], 0, v[130:131]
	s_add_i32 m0, s60, 0x2000
	s_nop 0
	global_load_lds_dwordx4 v[208:209], off
	v_lshl_add_u64 v[208:209], v[236:237], 0, s[20:21]
	s_mov_b32 m0, s34
	s_nop 0
	global_load_lds_dwordx4 v[208:209], off
	v_lshl_add_u64 v[208:209], v[238:239], 0, s[20:21]
	s_mov_b32 m0, s36
	s_nop 0
	global_load_lds_dwordx4 v[208:209], off
	s_waitcnt vmcnt(8)
	s_waitcnt lgkmcnt(0)
	s_barrier
	s_waitcnt lgkmcnt(0)
	v_mfma_f32_16x16x32_bf16 v[52:55], v[142:145], v[184:187], v[52:55]
	v_mfma_f32_16x16x32_bf16 v[48:51], v[160:163], v[184:187], v[48:51]
	v_mfma_f32_16x16x32_bf16 v[36:39], v[142:145], v[204:207], v[36:39]
	v_mfma_f32_16x16x32_bf16 v[32:35], v[160:163], v[204:207], v[32:35]
	v_mfma_f32_16x16x32_bf16 v[20:23], v[142:145], v[218:221], v[20:23]
	v_mfma_f32_16x16x32_bf16 v[16:19], v[160:163], v[218:221], v[16:19]
	v_mfma_f32_16x16x32_bf16 v[8:11], v[142:145], v[226:229], v[8:11]
	v_mfma_f32_16x16x32_bf16 v[0:3], v[160:163], v[226:229], v[0:3]
	v_mfma_f32_16x16x32_bf16 v[52:55], v[148:151], v[188:191], v[52:55]
	v_mfma_f32_16x16x32_bf16 v[48:51], v[164:167], v[188:191], v[48:51]
	v_mfma_f32_16x16x32_bf16 v[36:39], v[148:151], v[214:217], v[36:39]
	v_mfma_f32_16x16x32_bf16 v[32:35], v[164:167], v[214:217], v[32:35]
	v_mfma_f32_16x16x32_bf16 v[20:23], v[148:151], v[222:225], v[20:23]
	v_mfma_f32_16x16x32_bf16 v[16:19], v[164:167], v[222:225], v[16:19]
	v_mfma_f32_16x16x32_bf16 v[8:11], v[148:151], v[230:233], v[8:11]
	v_mfma_f32_16x16x32_bf16 v[0:3], v[164:167], v[230:233], v[0:3]
	v_mfma_f32_16x16x32_bf16 v[60:63], v[168:171], v[184:187], v[60:63]
	v_mfma_f32_16x16x32_bf16 v[56:59], v[176:179], v[184:187], v[56:59]
	v_mfma_f32_16x16x32_bf16 v[44:47], v[168:171], v[204:207], v[44:47]
	v_mfma_f32_16x16x32_bf16 v[40:43], v[176:179], v[204:207], v[40:43]
	v_mfma_f32_16x16x32_bf16 v[28:31], v[168:171], v[218:221], v[28:31]
	v_mfma_f32_16x16x32_bf16 v[24:27], v[176:179], v[218:221], v[24:27]
	v_mfma_f32_16x16x32_bf16 v[12:15], v[168:171], v[226:229], v[12:15]
	v_mfma_f32_16x16x32_bf16 v[4:7], v[176:179], v[226:229], v[4:7]
	v_mfma_f32_16x16x32_bf16 v[60:63], v[172:175], v[188:191], v[60:63]
	v_mfma_f32_16x16x32_bf16 v[56:59], v[180:183], v[188:191], v[56:59]
	v_mfma_f32_16x16x32_bf16 v[44:47], v[172:175], v[214:217], v[44:47]
	v_mfma_f32_16x16x32_bf16 v[40:43], v[180:183], v[214:217], v[40:43]
	v_mfma_f32_16x16x32_bf16 v[28:31], v[172:175], v[222:225], v[28:31]
	v_mfma_f32_16x16x32_bf16 v[24:27], v[180:183], v[222:225], v[24:27]
	v_mfma_f32_16x16x32_bf16 v[12:15], v[172:175], v[230:233], v[12:15]
	v_mfma_f32_16x16x32_bf16 v[4:7], v[180:183], v[230:233], v[4:7]
	s_barrier
	s_add_i32 s78, s78, 2
	s_add_u32 s46, s46, 0x100
	s_addc_u32 s47, s47, 0
	s_add_u32 s74, s74, 0x100
	s_addc_u32 s75, s75, 0
	s_cmp_gt_u32 s78, 13
	s_cbranch_scc0 .LBB0_227
	v_mov_b32_e32 v160, v192
	s_lshl_b32 s11, s67, 8
	v_mov_b32_e32 v151, v116
	v_ashrrev_i32_e32 v80, 2, v160
	v_and_b32_e32 v80, 0xffffffc0, v80
	v_and_or_b32 v142, v160, 15, s11
	v_add_u32_e32 v142, v142, v80
	v_ashrrev_i32_e32 v143, 31, v142
	v_lshl_add_u64 v[144:145], v[142:143], 2, s[90:91]
	v_add_co_u32_e32 v144, vcc, 0x40000, v144
	v_mov_b32_e32 v116, v125
	s_nop 0
	v_addc_co_u32_e32 v145, vcc, 0, v145, vcc
	global_load_dword v242, v[144:145], off
	global_load_dword v243, v[144:145], off offset:64
	global_load_dword v244, v[144:145], off offset:128
	global_load_dword v245, v[144:145], off offset:192
	global_load_dword v246, v[144:145], off offset:512
	global_load_dword v247, v[144:145], off offset:576
	global_load_dword v248, v[144:145], off offset:640
	global_load_dword v249, v[144:145], off offset:704
	s_and_b64 vcc, exec, s[6:7]
	s_cbranch_vccz .LBB0_230
	s_barrier

.LBB0_251:
	s_add_u32 s50, s46, 0xfffe0080
	s_addc_u32 s51, s47, -1
	s_add_i32 s73, 16, 0x10000
	s_cmp_eq_u32 s72, 4
	s_cselect_b32 s55, s15, s51
	s_cselect_b32 s54, s60, s50
	v_add_u32_e32 v146, s73, v80
	s_cselect_b32 s51, s11, s67
	s_cselect_b32 s50, s61, s66
	s_add_i32 s76, 16, 0x14000
	ds_read_b128 v[142:145], v146
	ds_read_b128 v[160:163], v146 offset:1024
	ds_read_b128 v[164:167], v146 offset:2048
	ds_read_b128 v[168:171], v146 offset:3072
	v_add_u32_e32 v146, s76, v80
	ds_read_b128 v[172:175], v146
	ds_read_b128 v[176:179], v146 offset:1024
	ds_read_b128 v[180:183], v146 offset:2048
	ds_read_b128 v[184:187], v146 offset:3072
	v_lshl_add_u64 v[146:147], s[46:47], 0, v[138:139]
	s_add_i32 m0, s13, 0xc000
	ds_read_b128 v[188:191], v148
	ds_read_b128 v[204:207], v148 offset:1024
	ds_read_b128 v[214:217], v148 offset:2048
	ds_read_b128 v[218:221], v148 offset:3072
	ds_read_b128 v[222:225], v148 offset:4096
	ds_read_b128 v[226:229], v148 offset:5120
	ds_read_b128 v[230:233], v148 offset:6144
	ds_read_b128 v[234:237], v148 offset:7168
	global_load_lds_dwordx4 v[146:147], off
	v_lshl_add_u64 v[146:147], s[46:47], 0, v[140:141]
	s_add_i32 m0, s13, 0xe000
	s_nop 0
	global_load_lds_dwordx4 v[146:147], off
	s_waitcnt vmcnt(8)
	s_waitcnt lgkmcnt(0)
	s_barrier
	s_waitcnt lgkmcnt(0)
	v_mfma_f32_16x16x32_bf16 v[126:129], v[142:145], v[188:191], v[126:129]
	v_mfma_f32_16x16x32_bf16 v[122:125], v[164:167], v[188:191], v[122:125]
	v_mfma_f32_16x16x32_bf16 v[110:113], v[142:145], v[214:217], v[110:113]
	v_mfma_f32_16x16x32_bf16 v[106:109], v[164:167], v[214:217], v[106:109]
	v_mfma_f32_16x16x32_bf16 v[94:97], v[142:145], v[222:225], v[94:97]
	v_mfma_f32_16x16x32_bf16 v[90:93], v[164:167], v[222:225], v[90:93]
	v_mfma_f32_16x16x32_bf16 v[76:79], v[142:145], v[230:233], v[76:79]
	v_mfma_f32_16x16x32_bf16 v[72:75], v[164:167], v[230:233], v[72:75]
	v_mfma_f32_16x16x32_bf16 v[126:129], v[160:163], v[204:207], v[126:129]
	v_mfma_f32_16x16x32_bf16 v[122:125], v[168:171], v[204:207], v[122:125]
	v_mfma_f32_16x16x32_bf16 v[110:113], v[160:163], v[218:221], v[110:113]
	v_mfma_f32_16x16x32_bf16 v[106:109], v[168:171], v[218:221], v[106:109]
	v_mfma_f32_16x16x32_bf16 v[94:97], v[160:163], v[226:229], v[94:97]
	v_mfma_f32_16x16x32_bf16 v[90:93], v[168:171], v[226:229], v[90:93]
	v_mfma_f32_16x16x32_bf16 v[76:79], v[160:163], v[234:237], v[76:79]
	v_mfma_f32_16x16x32_bf16 v[72:75], v[168:171], v[234:237], v[72:75]
	v_mfma_f32_16x16x32_bf16 v[118:121], v[172:175], v[188:191], v[118:121]
	v_mfma_f32_16x16x32_bf16 v[114:117], v[180:183], v[188:191], v[114:117]
	v_mfma_f32_16x16x32_bf16 v[102:105], v[172:175], v[214:217], v[102:105]
	v_mfma_f32_16x16x32_bf16 v[98:101], v[180:183], v[214:217], v[98:101]
	v_mfma_f32_16x16x32_bf16 v[86:89], v[172:175], v[222:225], v[86:89]
	v_mfma_f32_16x16x32_bf16 v[82:85], v[180:183], v[222:225], v[82:85]
	v_mfma_f32_16x16x32_bf16 v[68:71], v[172:175], v[230:233], v[68:71]
	v_mfma_f32_16x16x32_bf16 v[64:67], v[180:183], v[230:233], v[64:67]
	v_mfma_f32_16x16x32_bf16 v[118:121], v[176:179], v[204:207], v[118:121]
	v_mfma_f32_16x16x32_bf16 v[114:117], v[184:187], v[204:207], v[114:117]
	v_mfma_f32_16x16x32_bf16 v[102:105], v[176:179], v[218:221], v[102:105]
	v_mfma_f32_16x16x32_bf16 v[98:101], v[184:187], v[218:221], v[98:101]
	v_mfma_f32_16x16x32_bf16 v[86:89], v[176:179], v[226:229], v[86:89]
	v_mfma_f32_16x16x32_bf16 v[82:85], v[184:187], v[226:229], v[82:85]
	v_mfma_f32_16x16x32_bf16 v[68:71], v[176:179], v[234:237], v[68:71]
	v_mfma_f32_16x16x32_bf16 v[64:67], v[184:187], v[234:237], v[64:67]
	s_barrier
	s_add_i32 s73, s73, s4
	v_lshl_add_u64 v[146:147], s[50:51], 0, v[134:135]
	s_mov_b32 m0, s73
	ds_read_b128 v[188:191], v148 offset:16384
	ds_read_b128 v[204:207], v148 offset:17408
	ds_read_b128 v[214:217], v148 offset:18432
	ds_read_b128 v[218:221], v148 offset:19456
	ds_read_b128 v[222:225], v148 offset:20480
	ds_read_b128 v[226:229], v148 offset:21504
	ds_read_b128 v[230:233], v148 offset:22528
	ds_read_b128 v[234:237], v148 offset:23552
	global_load_lds_dwordx4 v[146:147], off
	s_add_i32 m0, s73, 0x2000
	s_add_u32 s74, s50, 0x20000
	v_lshl_add_u64 v[150:151], s[50:51], 0, v[130:131]
	s_addc_u32 s75, s51, 0
	s_add_i32 s73, s76, s4
	global_load_lds_dwordx4 v[150:151], off
	v_lshl_add_u64 v[208:209], s[74:75], 0, v[134:135]
	s_mov_b32 m0, s73
	v_lshl_add_u64 v[238:239], s[54:55], 0, v[132:133]
	global_load_lds_dwordx4 v[208:209], off
	v_lshl_add_u64 v[208:209], s[74:75], 0, v[130:131]
	s_add_i32 m0, s73, 0x2000
	s_nop 0
	global_load_lds_dwordx4 v[208:209], off
	v_lshl_add_u64 v[208:209], s[54:55], 0, v[136:137]
	s_mov_b32 m0, s13
	s_nop 0
	global_load_lds_dwordx4 v[208:209], off
	s_mov_b32 m0, s25
	s_nop 0
	global_load_lds_dwordx4 v[238:239], off
	s_waitcnt vmcnt(8)
	s_waitcnt lgkmcnt(0)
	s_barrier
	s_waitcnt lgkmcnt(0)
	v_mfma_f32_16x16x32_bf16 v[60:63], v[142:145], v[188:191], v[60:63]
	v_mfma_f32_16x16x32_bf16 v[56:59], v[164:167], v[188:191], v[56:59]
	v_mfma_f32_16x16x32_bf16 v[44:47], v[142:145], v[214:217], v[44:47]
	v_mfma_f32_16x16x32_bf16 v[40:43], v[164:167], v[214:217], v[40:43]
	v_mfma_f32_16x16x32_bf16 v[28:31], v[142:145], v[222:225], v[28:31]
	v_mfma_f32_16x16x32_bf16 v[24:27], v[164:167], v[222:225], v[24:27]
	v_mfma_f32_16x16x32_bf16 v[12:15], v[142:145], v[230:233], v[12:15]
	v_mfma_f32_16x16x32_bf16 v[8:11], v[164:167], v[230:233], v[8:11]
	v_mfma_f32_16x16x32_bf16 v[60:63], v[160:163], v[204:207], v[60:63]
	v_mfma_f32_16x16x32_bf16 v[56:59], v[168:171], v[204:207], v[56:59]
	v_mfma_f32_16x16x32_bf16 v[44:47], v[160:163], v[218:221], v[44:47]
	v_mfma_f32_16x16x32_bf16 v[40:43], v[168:171], v[218:221], v[40:43]
	v_mfma_f32_16x16x32_bf16 v[28:31], v[160:163], v[226:229], v[28:31]
	v_mfma_f32_16x16x32_bf16 v[24:27], v[168:171], v[226:229], v[24:27]
	v_mfma_f32_16x16x32_bf16 v[12:15], v[160:163], v[234:237], v[12:15]
	v_mfma_f32_16x16x32_bf16 v[8:11], v[168:171], v[234:237], v[8:11]
	v_mfma_f32_16x16x32_bf16 v[52:55], v[172:175], v[188:191], v[52:55]
	v_mfma_f32_16x16x32_bf16 v[48:51], v[180:183], v[188:191], v[48:51]
	v_mfma_f32_16x16x32_bf16 v[36:39], v[172:175], v[214:217], v[36:39]
	v_mfma_f32_16x16x32_bf16 v[32:35], v[180:183], v[214:217], v[32:35]
	v_mfma_f32_16x16x32_bf16 v[20:23], v[172:175], v[222:225], v[20:23]
	v_mfma_f32_16x16x32_bf16 v[16:19], v[180:183], v[222:225], v[16:19]
	v_mfma_f32_16x16x32_bf16 v[4:7], v[172:175], v[230:233], v[4:7]
	v_mfma_f32_16x16x32_bf16 v[0:3], v[180:183], v[230:233], v[0:3]
	v_mfma_f32_16x16x32_bf16 v[52:55], v[176:179], v[204:207], v[52:55]
	v_mfma_f32_16x16x32_bf16 v[48:51], v[184:187], v[204:207], v[48:51]
	v_mfma_f32_16x16x32_bf16 v[36:39], v[176:179], v[218:221], v[36:39]
	v_mfma_f32_16x16x32_bf16 v[32:35], v[184:187], v[218:221], v[32:35]
	v_mfma_f32_16x16x32_bf16 v[20:23], v[176:179], v[226:229], v[20:23]
	v_mfma_f32_16x16x32_bf16 v[16:19], v[184:187], v[226:229], v[16:19]
	v_mfma_f32_16x16x32_bf16 v[4:7], v[176:179], v[234:237], v[4:7]
	v_mfma_f32_16x16x32_bf16 v[0:3], v[184:187], v[234:237], v[0:3]
	s_barrier
	s_add_i32 s73, 16, 0x18000
	v_add_u32_e32 v149, s73, v80
	s_add_i32 s74, 16, 0x1c000
	ds_read_b128 v[142:145], v149
	ds_read_b128 v[160:163], v149 offset:1024
	ds_read_b128 v[164:167], v149 offset:2048
	ds_read_b128 v[168:171], v149 offset:3072
	v_add_u32_e32 v149, s74, v80
	ds_read_b128 v[172:175], v149
	ds_read_b128 v[176:179], v149 offset:1024
	ds_read_b128 v[180:183], v149 offset:2048
	ds_read_b128 v[184:187], v149 offset:3072
	s_add_u32 s54, s54, 0x20000
	s_addc_u32 s55, s55, 0
	s_mov_b32 m0, s30
	v_lshl_add_u64 v[240:241], s[54:55], 0, v[136:137]
	ds_read_b128 v[188:191], v148 offset:32768
	ds_read_b128 v[204:207], v148 offset:33792
	ds_read_b128 v[214:217], v148 offset:34816
	ds_read_b128 v[218:221], v148 offset:35840
	ds_read_b128 v[222:225], v148 offset:36864
	ds_read_b128 v[226:229], v148 offset:37888
	ds_read_b128 v[230:233], v148 offset:38912
	ds_read_b128 v[234:237], v148 offset:39936
	global_load_lds_dwordx4 v[240:241], off
	v_lshl_add_u64 v[240:241], s[54:55], 0, v[132:133]
	s_mov_b32 m0, s33
	s_nop 0
	global_load_lds_dwordx4 v[240:241], off
	s_waitcnt vmcnt(8)
	s_waitcnt lgkmcnt(0)
	s_barrier
	s_waitcnt lgkmcnt(0)
	v_mfma_f32_16x16x32_bf16 v[126:129], v[142:145], v[188:191], v[126:129]
	v_mfma_f32_16x16x32_bf16 v[122:125], v[164:167], v[188:191], v[122:125]
	v_mfma_f32_16x16x32_bf16 v[110:113], v[142:145], v[214:217], v[110:113]
	v_mfma_f32_16x16x32_bf16 v[106:109], v[164:167], v[214:217], v[106:109]
	v_mfma_f32_16x16x32_bf16 v[94:97], v[142:145], v[222:225], v[94:97]
	v_mfma_f32_16x16x32_bf16 v[90:93], v[164:167], v[222:225], v[90:93]
	v_mfma_f32_16x16x32_bf16 v[76:79], v[142:145], v[230:233], v[76:79]
	v_mfma_f32_16x16x32_bf16 v[72:75], v[164:167], v[230:233], v[72:75]
	v_mfma_f32_16x16x32_bf16 v[126:129], v[160:163], v[204:207], v[126:129]
	v_mfma_f32_16x16x32_bf16 v[122:125], v[168:171], v[204:207], v[122:125]
	v_mfma_f32_16x16x32_bf16 v[110:113], v[160:163], v[218:221], v[110:113]
	v_mfma_f32_16x16x32_bf16 v[106:109], v[168:171], v[218:221], v[106:109]
	v_mfma_f32_16x16x32_bf16 v[94:97], v[160:163], v[226:229], v[94:97]
	v_mfma_f32_16x16x32_bf16 v[90:93], v[168:171], v[226:229], v[90:93]
	v_mfma_f32_16x16x32_bf16 v[76:79], v[160:163], v[234:237], v[76:79]
	v_mfma_f32_16x16x32_bf16 v[72:75], v[168:171], v[234:237], v[72:75]
	v_mfma_f32_16x16x32_bf16 v[118:121], v[172:175], v[188:191], v[118:121]
	v_mfma_f32_16x16x32_bf16 v[114:117], v[180:183], v[188:191], v[114:117]
	v_mfma_f32_16x16x32_bf16 v[102:105], v[172:175], v[214:217], v[102:105]
	v_mfma_f32_16x16x32_bf16 v[98:101], v[180:183], v[214:217], v[98:101]
	v_mfma_f32_16x16x32_bf16 v[86:89], v[172:175], v[222:225], v[86:89]
	v_mfma_f32_16x16x32_bf16 v[82:85], v[180:183], v[222:225], v[82:85]
	v_mfma_f32_16x16x32_bf16 v[68:71], v[172:175], v[230:233], v[68:71]
	v_mfma_f32_16x16x32_bf16 v[64:67], v[180:183], v[230:233], v[64:67]
	v_mfma_f32_16x16x32_bf16 v[118:121], v[176:179], v[204:207], v[118:121]
	v_mfma_f32_16x16x32_bf16 v[114:117], v[184:187], v[204:207], v[114:117]
	v_mfma_f32_16x16x32_bf16 v[102:105], v[176:179], v[218:221], v[102:105]
	v_mfma_f32_16x16x32_bf16 v[98:101], v[184:187], v[218:221], v[98:101]
	v_mfma_f32_16x16x32_bf16 v[86:89], v[176:179], v[226:229], v[86:89]
	v_mfma_f32_16x16x32_bf16 v[82:85], v[184:187], v[226:229], v[82:85]
	v_mfma_f32_16x16x32_bf16 v[68:71], v[176:179], v[234:237], v[68:71]
	v_mfma_f32_16x16x32_bf16 v[64:67], v[184:187], v[234:237], v[64:67]
	s_barrier
	s_add_i32 s54, s73, s4
	v_lshl_add_u64 v[146:147], v[146:147], 0, s[20:21]
	s_mov_b32 m0, s54
	ds_read_b128 v[188:191], v148 offset:49152
	ds_read_b128 v[204:207], v148 offset:50176
	ds_read_b128 v[214:217], v148 offset:51200
	ds_read_b128 v[218:221], v148 offset:52224
	ds_read_b128 v[222:225], v148 offset:53248
	ds_read_b128 v[226:229], v148 offset:54272
	ds_read_b128 v[230:233], v148 offset:55296
	ds_read_b128 v[234:237], v148 offset:56320
	global_load_lds_dwordx4 v[146:147], off
	s_add_i32 m0, s54, 0x2000
	s_add_u32 s50, s50, 0x20080
	v_lshl_add_u64 v[146:147], v[150:151], 0, s[20:21]
	s_addc_u32 s51, s51, 0
	s_add_i32 s54, s74, s4
	global_load_lds_dwordx4 v[146:147], off
	v_lshl_add_u64 v[146:147], s[50:51], 0, v[134:135]
	s_mov_b32 m0, s54
	s_nop 0
	global_load_lds_dwordx4 v[146:147], off
	v_lshl_add_u64 v[146:147], s[50:51], 0, v[130:131]
	s_add_i32 m0, s54, 0x2000
	s_nop 0
	global_load_lds_dwordx4 v[146:147], off
	v_lshl_add_u64 v[146:147], v[208:209], 0, s[20:21]
	s_mov_b32 m0, s34
	s_nop 0
	global_load_lds_dwordx4 v[146:147], off
	v_lshl_add_u64 v[146:147], v[238:239], 0, s[20:21]
	s_mov_b32 m0, s36
	s_nop 0
	global_load_lds_dwordx4 v[146:147], off
	s_waitcnt vmcnt(8)
	s_waitcnt lgkmcnt(0)
	s_barrier
	s_waitcnt lgkmcnt(0)
	v_mfma_f32_16x16x32_bf16 v[60:63], v[142:145], v[188:191], v[60:63]
	v_mfma_f32_16x16x32_bf16 v[56:59], v[164:167], v[188:191], v[56:59]
	v_mfma_f32_16x16x32_bf16 v[44:47], v[142:145], v[214:217], v[44:47]
	v_mfma_f32_16x16x32_bf16 v[40:43], v[164:167], v[214:217], v[40:43]
	v_mfma_f32_16x16x32_bf16 v[28:31], v[142:145], v[222:225], v[28:31]
	v_mfma_f32_16x16x32_bf16 v[24:27], v[164:167], v[222:225], v[24:27]
	v_mfma_f32_16x16x32_bf16 v[12:15], v[142:145], v[230:233], v[12:15]
	v_mfma_f32_16x16x32_bf16 v[8:11], v[164:167], v[230:233], v[8:11]
	v_mfma_f32_16x16x32_bf16 v[60:63], v[160:163], v[204:207], v[60:63]
	v_mfma_f32_16x16x32_bf16 v[56:59], v[168:171], v[204:207], v[56:59]
	v_mfma_f32_16x16x32_bf16 v[44:47], v[160:163], v[218:221], v[44:47]
	v_mfma_f32_16x16x32_bf16 v[40:43], v[168:171], v[218:221], v[40:43]
	v_mfma_f32_16x16x32_bf16 v[28:31], v[160:163], v[226:229], v[28:31]
	v_mfma_f32_16x16x32_bf16 v[24:27], v[168:171], v[226:229], v[24:27]
	v_mfma_f32_16x16x32_bf16 v[12:15], v[160:163], v[234:237], v[12:15]
	v_mfma_f32_16x16x32_bf16 v[8:11], v[168:171], v[234:237], v[8:11]
	v_mfma_f32_16x16x32_bf16 v[52:55], v[172:175], v[188:191], v[52:55]
	v_mfma_f32_16x16x32_bf16 v[48:51], v[180:183], v[188:191], v[48:51]
	v_mfma_f32_16x16x32_bf16 v[36:39], v[172:175], v[214:217], v[36:39]
	v_mfma_f32_16x16x32_bf16 v[32:35], v[180:183], v[214:217], v[32:35]
	v_mfma_f32_16x16x32_bf16 v[20:23], v[172:175], v[222:225], v[20:23]
	v_mfma_f32_16x16x32_bf16 v[16:19], v[180:183], v[222:225], v[16:19]
	v_mfma_f32_16x16x32_bf16 v[4:7], v[172:175], v[230:233], v[4:7]
	v_mfma_f32_16x16x32_bf16 v[0:3], v[180:183], v[230:233], v[0:3]
	v_mfma_f32_16x16x32_bf16 v[52:55], v[176:179], v[204:207], v[52:55]
	v_mfma_f32_16x16x32_bf16 v[48:51], v[184:187], v[204:207], v[48:51]
	v_mfma_f32_16x16x32_bf16 v[36:39], v[176:179], v[218:221], v[36:39]
	v_mfma_f32_16x16x32_bf16 v[32:35], v[184:187], v[218:221], v[32:35]
	v_mfma_f32_16x16x32_bf16 v[20:23], v[176:179], v[226:229], v[20:23]
	v_mfma_f32_16x16x32_bf16 v[16:19], v[184:187], v[226:229], v[16:19]
	v_mfma_f32_16x16x32_bf16 v[4:7], v[176:179], v[234:237], v[4:7]
	v_mfma_f32_16x16x32_bf16 v[0:3], v[184:187], v[234:237], v[0:3]
	s_barrier
	s_add_i32 s72, s72, 2
	s_add_u32 s46, s46, 0x100
	s_addc_u32 s47, s47, 0
	s_add_u32 s66, s66, 0x100
	s_addc_u32 s67, s67, 0
	s_cmp_gt_u32 s72, 5
	s_cbranch_scc0 .LBB0_251
	s_and_b64 vcc, exec, s[6:7]
	s_cbranch_vccz .LBB0_254
	s_barrier

.LBB0_292:
	s_add_u32 s48, s46, 0xfffc0080
	s_addc_u32 s49, s47, -1
	s_add_i32 s60, 16, 0x10000
	s_cmp_eq_u32 s57, 12
	s_cselect_b32 s51, s11, s49
	s_cselect_b32 s50, s53, s48
	v_add_u32_e32 v80, s60, v186
	s_cselect_b32 s49, s43, s56
	s_cselect_b32 s48, s54, s55
	s_add_i32 s67, 16, 0x14000
	ds_read_b128 v[130:133], v80
	ds_read_b128 v[134:137], v80 offset:1024
	ds_read_b128 v[138:141], v80 offset:2048
	ds_read_b128 v[162:165], v80 offset:3072
	v_add_u32_e32 v80, s67, v186
	ds_read_b128 v[166:169], v80
	ds_read_b128 v[170:173], v80 offset:1024
	ds_read_b128 v[174:177], v80 offset:2048
	ds_read_b128 v[178:181], v80 offset:3072
	v_lshl_add_u64 v[208:209], s[46:47], 0, v[150:151]
	s_add_i32 m0, s25, 0xc000
	ds_read_b128 v[182:185], v187
	ds_read_b128 v[188:191], v187 offset:1024
	ds_read_b128 v[204:207], v187 offset:2048
	ds_read_b128 v[214:217], v187 offset:3072
	ds_read_b128 v[218:221], v187 offset:4096
	ds_read_b128 v[222:225], v187 offset:5120
	ds_read_b128 v[226:229], v187 offset:6144
	ds_read_b128 v[230:233], v187 offset:7168
	global_load_lds_dwordx4 v[208:209], off
	v_lshl_add_u64 v[208:209], s[46:47], 0, v[160:161]
	s_add_i32 m0, s25, 0xe000
	s_nop 0
	global_load_lds_dwordx4 v[208:209], off
	s_waitcnt vmcnt(8)
	s_waitcnt lgkmcnt(0)
	s_barrier
	s_waitcnt lgkmcnt(0)
	v_mfma_f32_16x16x32_bf16 v[126:129], v[130:133], v[182:185], v[126:129]
	v_mfma_f32_16x16x32_bf16 v[122:125], v[138:141], v[182:185], v[122:125]
	v_mfma_f32_16x16x32_bf16 v[110:113], v[130:133], v[204:207], v[110:113]
	v_mfma_f32_16x16x32_bf16 v[106:109], v[138:141], v[204:207], v[106:109]
	v_mfma_f32_16x16x32_bf16 v[94:97], v[130:133], v[218:221], v[94:97]
	v_mfma_f32_16x16x32_bf16 v[90:93], v[138:141], v[218:221], v[90:93]
	v_mfma_f32_16x16x32_bf16 v[76:79], v[130:133], v[226:229], v[76:79]
	v_mfma_f32_16x16x32_bf16 v[72:75], v[138:141], v[226:229], v[72:75]
	v_mfma_f32_16x16x32_bf16 v[126:129], v[134:137], v[188:191], v[126:129]
	v_mfma_f32_16x16x32_bf16 v[122:125], v[162:165], v[188:191], v[122:125]
	v_mfma_f32_16x16x32_bf16 v[110:113], v[134:137], v[214:217], v[110:113]
	v_mfma_f32_16x16x32_bf16 v[106:109], v[162:165], v[214:217], v[106:109]
	v_mfma_f32_16x16x32_bf16 v[94:97], v[134:137], v[222:225], v[94:97]
	v_mfma_f32_16x16x32_bf16 v[90:93], v[162:165], v[222:225], v[90:93]
	v_mfma_f32_16x16x32_bf16 v[76:79], v[134:137], v[230:233], v[76:79]
	v_mfma_f32_16x16x32_bf16 v[72:75], v[162:165], v[230:233], v[72:75]
	v_mfma_f32_16x16x32_bf16 v[118:121], v[166:169], v[182:185], v[118:121]
	v_mfma_f32_16x16x32_bf16 v[114:117], v[174:177], v[182:185], v[114:117]
	v_mfma_f32_16x16x32_bf16 v[102:105], v[166:169], v[204:207], v[102:105]
	v_mfma_f32_16x16x32_bf16 v[98:101], v[174:177], v[204:207], v[98:101]
	v_mfma_f32_16x16x32_bf16 v[86:89], v[166:169], v[218:221], v[86:89]
	v_mfma_f32_16x16x32_bf16 v[82:85], v[174:177], v[218:221], v[82:85]
	v_mfma_f32_16x16x32_bf16 v[68:71], v[166:169], v[226:229], v[68:71]
	v_mfma_f32_16x16x32_bf16 v[64:67], v[174:177], v[226:229], v[64:67]
	v_mfma_f32_16x16x32_bf16 v[118:121], v[170:173], v[188:191], v[118:121]
	v_mfma_f32_16x16x32_bf16 v[114:117], v[178:181], v[188:191], v[114:117]
	v_mfma_f32_16x16x32_bf16 v[102:105], v[170:173], v[214:217], v[102:105]
	v_mfma_f32_16x16x32_bf16 v[98:101], v[178:181], v[214:217], v[98:101]
	v_mfma_f32_16x16x32_bf16 v[86:89], v[170:173], v[222:225], v[86:89]
	v_mfma_f32_16x16x32_bf16 v[82:85], v[178:181], v[222:225], v[82:85]
	v_mfma_f32_16x16x32_bf16 v[68:71], v[170:173], v[230:233], v[68:71]
	v_mfma_f32_16x16x32_bf16 v[64:67], v[178:181], v[230:233], v[64:67]
	s_barrier
	s_add_i32 s60, s60, s13
	v_lshl_add_u64 v[208:209], s[48:49], 0, v[146:147]
	s_mov_b32 m0, s60
	ds_read_b128 v[182:185], v187 offset:16384
	ds_read_b128 v[188:191], v187 offset:17408
	ds_read_b128 v[204:207], v187 offset:18432
	ds_read_b128 v[214:217], v187 offset:19456
	ds_read_b128 v[218:221], v187 offset:20480
	ds_read_b128 v[222:225], v187 offset:21504
	ds_read_b128 v[226:229], v187 offset:22528
	ds_read_b128 v[230:233], v187 offset:23552
	global_load_lds_dwordx4 v[208:209], off
	s_add_i32 m0, s60, 0x2000
	s_add_u32 s60, s48, 0x40000
	v_lshl_add_u64 v[234:235], s[48:49], 0, v[142:143]
	s_addc_u32 s61, s49, 0
	s_add_i32 s67, s67, s13
	global_load_lds_dwordx4 v[234:235], off
	v_lshl_add_u64 v[236:237], s[60:61], 0, v[146:147]
	s_mov_b32 m0, s67
	v_lshl_add_u64 v[238:239], s[50:51], 0, v[144:145]
	global_load_lds_dwordx4 v[236:237], off
	v_lshl_add_u64 v[236:237], s[60:61], 0, v[142:143]
	s_add_i32 m0, s67, 0x2000
	s_nop 0
	global_load_lds_dwordx4 v[236:237], off
	v_lshl_add_u64 v[236:237], s[50:51], 0, v[148:149]
	s_mov_b32 m0, s25
	s_nop 0
	global_load_lds_dwordx4 v[236:237], off
	s_mov_b32 m0, s30
	s_nop 0
	global_load_lds_dwordx4 v[238:239], off
	s_waitcnt vmcnt(8)
	s_waitcnt lgkmcnt(0)
	s_barrier
	s_waitcnt lgkmcnt(0)
	v_mfma_f32_16x16x32_bf16 v[60:63], v[130:133], v[182:185], v[60:63]
	v_mfma_f32_16x16x32_bf16 v[56:59], v[138:141], v[182:185], v[56:59]
	v_mfma_f32_16x16x32_bf16 v[44:47], v[130:133], v[204:207], v[44:47]
	v_mfma_f32_16x16x32_bf16 v[40:43], v[138:141], v[204:207], v[40:43]
	v_mfma_f32_16x16x32_bf16 v[28:31], v[130:133], v[218:221], v[28:31]
	v_mfma_f32_16x16x32_bf16 v[24:27], v[138:141], v[218:221], v[24:27]
	v_mfma_f32_16x16x32_bf16 v[12:15], v[130:133], v[226:229], v[12:15]
	v_mfma_f32_16x16x32_bf16 v[8:11], v[138:141], v[226:229], v[8:11]
	v_mfma_f32_16x16x32_bf16 v[60:63], v[134:137], v[188:191], v[60:63]
	v_mfma_f32_16x16x32_bf16 v[56:59], v[162:165], v[188:191], v[56:59]
	v_mfma_f32_16x16x32_bf16 v[44:47], v[134:137], v[214:217], v[44:47]
	v_mfma_f32_16x16x32_bf16 v[40:43], v[162:165], v[214:217], v[40:43]
	v_mfma_f32_16x16x32_bf16 v[28:31], v[134:137], v[222:225], v[28:31]
	v_mfma_f32_16x16x32_bf16 v[24:27], v[162:165], v[222:225], v[24:27]
	v_mfma_f32_16x16x32_bf16 v[12:15], v[134:137], v[230:233], v[12:15]
	v_mfma_f32_16x16x32_bf16 v[8:11], v[162:165], v[230:233], v[8:11]
	v_mfma_f32_16x16x32_bf16 v[52:55], v[166:169], v[182:185], v[52:55]
	v_mfma_f32_16x16x32_bf16 v[48:51], v[174:177], v[182:185], v[48:51]
	v_mfma_f32_16x16x32_bf16 v[36:39], v[166:169], v[204:207], v[36:39]
	v_mfma_f32_16x16x32_bf16 v[32:35], v[174:177], v[204:207], v[32:35]
	v_mfma_f32_16x16x32_bf16 v[20:23], v[166:169], v[218:221], v[20:23]
	v_mfma_f32_16x16x32_bf16 v[16:19], v[174:177], v[218:221], v[16:19]
	v_mfma_f32_16x16x32_bf16 v[4:7], v[166:169], v[226:229], v[4:7]
	v_mfma_f32_16x16x32_bf16 v[0:3], v[174:177], v[226:229], v[0:3]
	v_mfma_f32_16x16x32_bf16 v[52:55], v[170:173], v[188:191], v[52:55]
	v_mfma_f32_16x16x32_bf16 v[48:51], v[178:181], v[188:191], v[48:51]
	v_mfma_f32_16x16x32_bf16 v[36:39], v[170:173], v[214:217], v[36:39]
	v_mfma_f32_16x16x32_bf16 v[32:35], v[178:181], v[214:217], v[32:35]
	v_mfma_f32_16x16x32_bf16 v[20:23], v[170:173], v[222:225], v[20:23]
	v_mfma_f32_16x16x32_bf16 v[16:19], v[178:181], v[222:225], v[16:19]
	v_mfma_f32_16x16x32_bf16 v[4:7], v[170:173], v[230:233], v[4:7]
	v_mfma_f32_16x16x32_bf16 v[0:3], v[178:181], v[230:233], v[0:3]
	s_barrier
	s_add_i32 s60, 16, 0x18000
	v_add_u32_e32 v80, s60, v186
	s_add_i32 s61, 16, 0x1c000
	ds_read_b128 v[130:133], v80
	ds_read_b128 v[134:137], v80 offset:1024
	ds_read_b128 v[138:141], v80 offset:2048
	ds_read_b128 v[162:165], v80 offset:3072
	v_add_u32_e32 v80, s61, v186
	ds_read_b128 v[166:169], v80
	ds_read_b128 v[170:173], v80 offset:1024
	ds_read_b128 v[174:177], v80 offset:2048
	ds_read_b128 v[178:181], v80 offset:3072
	s_add_u32 s50, s50, 0x40000
	s_addc_u32 s51, s51, 0
	s_mov_b32 m0, s33
	v_lshl_add_u64 v[240:241], s[50:51], 0, v[148:149]
	ds_read_b128 v[182:185], v187 offset:32768
	ds_read_b128 v[188:191], v187 offset:33792
	ds_read_b128 v[204:207], v187 offset:34816
	ds_read_b128 v[214:217], v187 offset:35840
	ds_read_b128 v[218:221], v187 offset:36864
	ds_read_b128 v[222:225], v187 offset:37888
	ds_read_b128 v[226:229], v187 offset:38912
	ds_read_b128 v[230:233], v187 offset:39936
	global_load_lds_dwordx4 v[240:241], off
	v_lshl_add_u64 v[240:241], s[50:51], 0, v[144:145]
	s_mov_b32 m0, s34
	s_nop 0
	global_load_lds_dwordx4 v[240:241], off
	s_waitcnt vmcnt(8)
	s_waitcnt lgkmcnt(0)
	s_barrier
	s_waitcnt lgkmcnt(0)
	v_mfma_f32_16x16x32_bf16 v[126:129], v[130:133], v[182:185], v[126:129]
	v_mfma_f32_16x16x32_bf16 v[122:125], v[138:141], v[182:185], v[122:125]
	v_mfma_f32_16x16x32_bf16 v[110:113], v[130:133], v[204:207], v[110:113]
	v_mfma_f32_16x16x32_bf16 v[106:109], v[138:141], v[204:207], v[106:109]
	v_mfma_f32_16x16x32_bf16 v[94:97], v[130:133], v[218:221], v[94:97]
	v_mfma_f32_16x16x32_bf16 v[90:93], v[138:141], v[218:221], v[90:93]
	v_mfma_f32_16x16x32_bf16 v[76:79], v[130:133], v[226:229], v[76:79]
	v_mfma_f32_16x16x32_bf16 v[72:75], v[138:141], v[226:229], v[72:75]
	v_mfma_f32_16x16x32_bf16 v[126:129], v[134:137], v[188:191], v[126:129]
	v_mfma_f32_16x16x32_bf16 v[122:125], v[162:165], v[188:191], v[122:125]
	v_mfma_f32_16x16x32_bf16 v[110:113], v[134:137], v[214:217], v[110:113]
	v_mfma_f32_16x16x32_bf16 v[106:109], v[162:165], v[214:217], v[106:109]
	v_mfma_f32_16x16x32_bf16 v[94:97], v[134:137], v[222:225], v[94:97]
	v_mfma_f32_16x16x32_bf16 v[90:93], v[162:165], v[222:225], v[90:93]
	v_mfma_f32_16x16x32_bf16 v[76:79], v[134:137], v[230:233], v[76:79]
	v_mfma_f32_16x16x32_bf16 v[72:75], v[162:165], v[230:233], v[72:75]
	v_mfma_f32_16x16x32_bf16 v[118:121], v[166:169], v[182:185], v[118:121]
	v_mfma_f32_16x16x32_bf16 v[114:117], v[174:177], v[182:185], v[114:117]
	v_mfma_f32_16x16x32_bf16 v[102:105], v[166:169], v[204:207], v[102:105]
	v_mfma_f32_16x16x32_bf16 v[98:101], v[174:177], v[204:207], v[98:101]
	v_mfma_f32_16x16x32_bf16 v[86:89], v[166:169], v[218:221], v[86:89]
	v_mfma_f32_16x16x32_bf16 v[82:85], v[174:177], v[218:221], v[82:85]
	v_mfma_f32_16x16x32_bf16 v[68:71], v[166:169], v[226:229], v[68:71]
	v_mfma_f32_16x16x32_bf16 v[64:67], v[174:177], v[226:229], v[64:67]
	v_mfma_f32_16x16x32_bf16 v[118:121], v[170:173], v[188:191], v[118:121]
	v_mfma_f32_16x16x32_bf16 v[114:117], v[178:181], v[188:191], v[114:117]
	v_mfma_f32_16x16x32_bf16 v[102:105], v[170:173], v[214:217], v[102:105]
	v_mfma_f32_16x16x32_bf16 v[98:101], v[178:181], v[214:217], v[98:101]
	v_mfma_f32_16x16x32_bf16 v[86:89], v[170:173], v[222:225], v[86:89]
	v_mfma_f32_16x16x32_bf16 v[82:85], v[178:181], v[222:225], v[82:85]
	v_mfma_f32_16x16x32_bf16 v[68:71], v[170:173], v[230:233], v[68:71]
	v_mfma_f32_16x16x32_bf16 v[64:67], v[178:181], v[230:233], v[64:67]
	s_barrier
	s_add_i32 s50, s60, s13
	v_lshl_add_u64 v[208:209], v[208:209], 0, s[20:21]
	s_mov_b32 m0, s50
	ds_read_b128 v[182:185], v187 offset:49152
	ds_read_b128 v[188:191], v187 offset:50176
	ds_read_b128 v[204:207], v187 offset:51200
	ds_read_b128 v[214:217], v187 offset:52224
	ds_read_b128 v[218:221], v187 offset:53248
	ds_read_b128 v[222:225], v187 offset:54272
	ds_read_b128 v[226:229], v187 offset:55296
	ds_read_b128 v[230:233], v187 offset:56320
	global_load_lds_dwordx4 v[208:209], off
	s_add_i32 m0, s50, 0x2000
	s_add_u32 s48, s48, 0x40080
	v_lshl_add_u64 v[208:209], v[234:235], 0, s[20:21]
	s_addc_u32 s49, s49, 0
	s_add_i32 s50, s61, s13
	global_load_lds_dwordx4 v[208:209], off
	v_lshl_add_u64 v[208:209], s[48:49], 0, v[146:147]
	s_mov_b32 m0, s50
	s_nop 0
	global_load_lds_dwordx4 v[208:209], off
	v_lshl_add_u64 v[208:209], s[48:49], 0, v[142:143]
	s_add_i32 m0, s50, 0x2000
	s_nop 0
	global_load_lds_dwordx4 v[208:209], off
	v_lshl_add_u64 v[208:209], v[236:237], 0, s[20:21]
	s_mov_b32 m0, s36
	s_nop 0
	global_load_lds_dwordx4 v[208:209], off
	v_lshl_add_u64 v[208:209], v[238:239], 0, s[20:21]
	s_mov_b32 m0, s37
	s_nop 0
	global_load_lds_dwordx4 v[208:209], off
	s_waitcnt vmcnt(8)
	s_waitcnt lgkmcnt(0)
	s_barrier
	s_waitcnt lgkmcnt(0)
	v_mfma_f32_16x16x32_bf16 v[60:63], v[130:133], v[182:185], v[60:63]
	v_mfma_f32_16x16x32_bf16 v[56:59], v[138:141], v[182:185], v[56:59]
	v_mfma_f32_16x16x32_bf16 v[44:47], v[130:133], v[204:207], v[44:47]
	v_mfma_f32_16x16x32_bf16 v[40:43], v[138:141], v[204:207], v[40:43]
	v_mfma_f32_16x16x32_bf16 v[28:31], v[130:133], v[218:221], v[28:31]
	v_mfma_f32_16x16x32_bf16 v[24:27], v[138:141], v[218:221], v[24:27]
	v_mfma_f32_16x16x32_bf16 v[12:15], v[130:133], v[226:229], v[12:15]
	v_mfma_f32_16x16x32_bf16 v[8:11], v[138:141], v[226:229], v[8:11]
	v_mfma_f32_16x16x32_bf16 v[60:63], v[134:137], v[188:191], v[60:63]
	v_mfma_f32_16x16x32_bf16 v[56:59], v[162:165], v[188:191], v[56:59]
	v_mfma_f32_16x16x32_bf16 v[44:47], v[134:137], v[214:217], v[44:47]
	v_mfma_f32_16x16x32_bf16 v[40:43], v[162:165], v[214:217], v[40:43]
	v_mfma_f32_16x16x32_bf16 v[28:31], v[134:137], v[222:225], v[28:31]
	v_mfma_f32_16x16x32_bf16 v[24:27], v[162:165], v[222:225], v[24:27]
	v_mfma_f32_16x16x32_bf16 v[12:15], v[134:137], v[230:233], v[12:15]
	v_mfma_f32_16x16x32_bf16 v[8:11], v[162:165], v[230:233], v[8:11]
	v_mfma_f32_16x16x32_bf16 v[52:55], v[166:169], v[182:185], v[52:55]
	v_mfma_f32_16x16x32_bf16 v[48:51], v[174:177], v[182:185], v[48:51]
	v_mfma_f32_16x16x32_bf16 v[36:39], v[166:169], v[204:207], v[36:39]
	v_mfma_f32_16x16x32_bf16 v[32:35], v[174:177], v[204:207], v[32:35]
	v_mfma_f32_16x16x32_bf16 v[20:23], v[166:169], v[218:221], v[20:23]
	v_mfma_f32_16x16x32_bf16 v[16:19], v[174:177], v[218:221], v[16:19]
	v_mfma_f32_16x16x32_bf16 v[4:7], v[166:169], v[226:229], v[4:7]
	v_mfma_f32_16x16x32_bf16 v[0:3], v[174:177], v[226:229], v[0:3]
	v_mfma_f32_16x16x32_bf16 v[52:55], v[170:173], v[188:191], v[52:55]
	v_mfma_f32_16x16x32_bf16 v[48:51], v[178:181], v[188:191], v[48:51]
	v_mfma_f32_16x16x32_bf16 v[36:39], v[170:173], v[214:217], v[36:39]
	v_mfma_f32_16x16x32_bf16 v[32:35], v[178:181], v[214:217], v[32:35]
	v_mfma_f32_16x16x32_bf16 v[20:23], v[170:173], v[222:225], v[20:23]
	v_mfma_f32_16x16x32_bf16 v[16:19], v[178:181], v[222:225], v[16:19]
	v_mfma_f32_16x16x32_bf16 v[4:7], v[170:173], v[230:233], v[4:7]
	v_mfma_f32_16x16x32_bf16 v[0:3], v[178:181], v[230:233], v[0:3]
	s_barrier
	s_add_i32 s57, s57, 2
	s_add_u32 s46, s46, 0x100
	s_addc_u32 s47, s47, 0
	s_add_u32 s55, s55, 0x100
	s_addc_u32 s56, s56, 0
	s_cmp_gt_u32 s57, 13
	s_cbranch_scc0 .LBB0_292
	s_and_b64 vcc, exec, s[6:7]
	s_cbranch_vccz .LBB0_295
	s_barrier

.LBB0_640:
	s_add_u32 s44, s42, 0x100
	s_addc_u32 s45, s43, 0
	s_add_i32 s57, 16, 0x10000
	s_cmp_eq_u32 s56, 40
	s_cselect_b32 s49, s11, s45
	s_cselect_b32 s48, s10, s44
	v_add_u32_e32 v80, s57, v144
	s_cselect_b32 s47, s15, s55
	s_cselect_b32 s46, s14, s54
	s_add_i32 s60, 16, 0x14000
	ds_read_b128 v[146:149], v80
	ds_read_b128 v[160:163], v80 offset:1024
	ds_read_b128 v[164:167], v80 offset:2048
	ds_read_b128 v[168:171], v80 offset:3072
	v_add_u32_e32 v80, s60, v144
	ds_read_b128 v[172:175], v80
	ds_read_b128 v[176:179], v80 offset:1024
	ds_read_b128 v[180:183], v80 offset:2048
	ds_read_b128 v[184:187], v80 offset:3072
	v_lshl_add_u64 v[142:143], s[42:43], 0, v[138:139]
	s_add_i32 m0, s13, 0xc000
	ds_read_b128 v[188:191], v145
	ds_read_b128 v[204:207], v145 offset:1024
	ds_read_b128 v[214:217], v145 offset:2048
	ds_read_b128 v[218:221], v145 offset:3072
	ds_read_b128 v[222:225], v145 offset:4096
	ds_read_b128 v[226:229], v145 offset:5120
	ds_read_b128 v[230:233], v145 offset:6144
	ds_read_b128 v[234:237], v145 offset:7168
	global_load_lds_dwordx4 v[142:143], off
	v_lshl_add_u64 v[142:143], s[42:43], 0, v[140:141]
	s_add_i32 m0, s13, 0xe000
	s_nop 0
	global_load_lds_dwordx4 v[142:143], off
	s_waitcnt vmcnt(8)
	s_waitcnt lgkmcnt(0)
	s_barrier
	s_waitcnt lgkmcnt(0)
	v_mfma_f32_16x16x32_bf16 v[126:129], v[146:149], v[188:191], v[126:129]
	v_mfma_f32_16x16x32_bf16 v[122:125], v[164:167], v[188:191], v[122:125]
	v_mfma_f32_16x16x32_bf16 v[110:113], v[146:149], v[214:217], v[110:113]
	v_mfma_f32_16x16x32_bf16 v[106:109], v[164:167], v[214:217], v[106:109]
	v_mfma_f32_16x16x32_bf16 v[94:97], v[146:149], v[222:225], v[94:97]
	v_mfma_f32_16x16x32_bf16 v[90:93], v[164:167], v[222:225], v[90:93]
	v_mfma_f32_16x16x32_bf16 v[76:79], v[146:149], v[230:233], v[76:79]
	v_mfma_f32_16x16x32_bf16 v[72:75], v[164:167], v[230:233], v[72:75]
	v_mfma_f32_16x16x32_bf16 v[126:129], v[160:163], v[204:207], v[126:129]
	v_mfma_f32_16x16x32_bf16 v[122:125], v[168:171], v[204:207], v[122:125]
	v_mfma_f32_16x16x32_bf16 v[110:113], v[160:163], v[218:221], v[110:113]
	v_mfma_f32_16x16x32_bf16 v[106:109], v[168:171], v[218:221], v[106:109]
	v_mfma_f32_16x16x32_bf16 v[94:97], v[160:163], v[226:229], v[94:97]
	v_mfma_f32_16x16x32_bf16 v[90:93], v[168:171], v[226:229], v[90:93]
	v_mfma_f32_16x16x32_bf16 v[76:79], v[160:163], v[234:237], v[76:79]
	v_mfma_f32_16x16x32_bf16 v[72:75], v[168:171], v[234:237], v[72:75]
	v_mfma_f32_16x16x32_bf16 v[118:121], v[172:175], v[188:191], v[118:121]
	v_mfma_f32_16x16x32_bf16 v[114:117], v[180:183], v[188:191], v[114:117]
	v_mfma_f32_16x16x32_bf16 v[102:105], v[172:175], v[214:217], v[102:105]
	v_mfma_f32_16x16x32_bf16 v[98:101], v[180:183], v[214:217], v[98:101]
	v_mfma_f32_16x16x32_bf16 v[86:89], v[172:175], v[222:225], v[86:89]
	v_mfma_f32_16x16x32_bf16 v[82:85], v[180:183], v[222:225], v[82:85]
	v_mfma_f32_16x16x32_bf16 v[68:71], v[172:175], v[230:233], v[68:71]
	v_mfma_f32_16x16x32_bf16 v[64:67], v[180:183], v[230:233], v[64:67]
	v_mfma_f32_16x16x32_bf16 v[118:121], v[176:179], v[204:207], v[118:121]
	v_mfma_f32_16x16x32_bf16 v[114:117], v[184:187], v[204:207], v[114:117]
	v_mfma_f32_16x16x32_bf16 v[102:105], v[176:179], v[218:221], v[102:105]
	v_mfma_f32_16x16x32_bf16 v[98:101], v[184:187], v[218:221], v[98:101]
	v_mfma_f32_16x16x32_bf16 v[86:89], v[176:179], v[226:229], v[86:89]
	v_mfma_f32_16x16x32_bf16 v[82:85], v[184:187], v[226:229], v[82:85]
	v_mfma_f32_16x16x32_bf16 v[68:71], v[176:179], v[234:237], v[68:71]
	v_mfma_f32_16x16x32_bf16 v[64:67], v[184:187], v[234:237], v[64:67]
	s_barrier
	s_add_i32 s42, s57, s4
	v_lshl_add_u64 v[142:143], s[46:47], 0, v[134:135]
	s_mov_b32 m0, s42
	ds_read_b128 v[188:191], v145 offset:16384
	ds_read_b128 v[204:207], v145 offset:17408
	ds_read_b128 v[214:217], v145 offset:18432
	ds_read_b128 v[218:221], v145 offset:19456
	ds_read_b128 v[222:225], v145 offset:20480
	ds_read_b128 v[226:229], v145 offset:21504
	ds_read_b128 v[230:233], v145 offset:22528
	ds_read_b128 v[234:237], v145 offset:23552
	global_load_lds_dwordx4 v[142:143], off
	s_add_i32 m0, s42, 0x2000
	s_add_u32 s42, s46, 0xb0000
	v_lshl_add_u64 v[150:151], s[46:47], 0, v[130:131]
	s_addc_u32 s43, s47, 0
	s_add_i32 s57, s60, s4
	global_load_lds_dwordx4 v[150:151], off
	v_lshl_add_u64 v[208:209], s[42:43], 0, v[134:135]
	s_mov_b32 m0, s57
	v_lshl_add_u64 v[238:239], s[48:49], 0, v[132:133]
	global_load_lds_dwordx4 v[208:209], off
	v_lshl_add_u64 v[208:209], s[42:43], 0, v[130:131]
	s_add_i32 m0, s57, 0x2000
	s_nop 0
	global_load_lds_dwordx4 v[208:209], off
	v_lshl_add_u64 v[208:209], s[48:49], 0, v[136:137]
	s_mov_b32 m0, s13
	s_nop 0
	global_load_lds_dwordx4 v[208:209], off
	s_mov_b32 m0, s25
	s_nop 0
	global_load_lds_dwordx4 v[238:239], off
	s_waitcnt vmcnt(8)
	s_waitcnt lgkmcnt(0)
	s_barrier
	s_waitcnt lgkmcnt(0)
	v_mfma_f32_16x16x32_bf16 v[60:63], v[146:149], v[188:191], v[60:63]
	v_mfma_f32_16x16x32_bf16 v[56:59], v[164:167], v[188:191], v[56:59]
	v_mfma_f32_16x16x32_bf16 v[44:47], v[146:149], v[214:217], v[44:47]
	v_mfma_f32_16x16x32_bf16 v[40:43], v[164:167], v[214:217], v[40:43]
	v_mfma_f32_16x16x32_bf16 v[28:31], v[146:149], v[222:225], v[28:31]
	v_mfma_f32_16x16x32_bf16 v[24:27], v[164:167], v[222:225], v[24:27]
	v_mfma_f32_16x16x32_bf16 v[12:15], v[146:149], v[230:233], v[12:15]
	v_mfma_f32_16x16x32_bf16 v[8:11], v[164:167], v[230:233], v[8:11]
	v_mfma_f32_16x16x32_bf16 v[60:63], v[160:163], v[204:207], v[60:63]
	v_mfma_f32_16x16x32_bf16 v[56:59], v[168:171], v[204:207], v[56:59]
	v_mfma_f32_16x16x32_bf16 v[44:47], v[160:163], v[218:221], v[44:47]
	v_mfma_f32_16x16x32_bf16 v[40:43], v[168:171], v[218:221], v[40:43]
	v_mfma_f32_16x16x32_bf16 v[28:31], v[160:163], v[226:229], v[28:31]
	v_mfma_f32_16x16x32_bf16 v[24:27], v[168:171], v[226:229], v[24:27]
	v_mfma_f32_16x16x32_bf16 v[12:15], v[160:163], v[234:237], v[12:15]
	v_mfma_f32_16x16x32_bf16 v[8:11], v[168:171], v[234:237], v[8:11]
	v_mfma_f32_16x16x32_bf16 v[52:55], v[172:175], v[188:191], v[52:55]
	v_mfma_f32_16x16x32_bf16 v[48:51], v[180:183], v[188:191], v[48:51]
	v_mfma_f32_16x16x32_bf16 v[36:39], v[172:175], v[214:217], v[36:39]
	v_mfma_f32_16x16x32_bf16 v[32:35], v[180:183], v[214:217], v[32:35]
	v_mfma_f32_16x16x32_bf16 v[20:23], v[172:175], v[222:225], v[20:23]
	v_mfma_f32_16x16x32_bf16 v[16:19], v[180:183], v[222:225], v[16:19]
	v_mfma_f32_16x16x32_bf16 v[4:7], v[172:175], v[230:233], v[4:7]
	v_mfma_f32_16x16x32_bf16 v[0:3], v[180:183], v[230:233], v[0:3]
	v_mfma_f32_16x16x32_bf16 v[52:55], v[176:179], v[204:207], v[52:55]
	v_mfma_f32_16x16x32_bf16 v[48:51], v[184:187], v[204:207], v[48:51]
	v_mfma_f32_16x16x32_bf16 v[36:39], v[176:179], v[218:221], v[36:39]
	v_mfma_f32_16x16x32_bf16 v[32:35], v[184:187], v[218:221], v[32:35]
	v_mfma_f32_16x16x32_bf16 v[20:23], v[176:179], v[226:229], v[20:23]
	v_mfma_f32_16x16x32_bf16 v[16:19], v[184:187], v[226:229], v[16:19]
	v_mfma_f32_16x16x32_bf16 v[4:7], v[176:179], v[234:237], v[4:7]
	v_mfma_f32_16x16x32_bf16 v[0:3], v[184:187], v[234:237], v[0:3]
	s_barrier
	s_add_i32 s57, 16, 0x18000
	v_add_u32_e32 v80, s57, v144
	s_add_i32 s60, 16, 0x1c000
	ds_read_b128 v[146:149], v80
	ds_read_b128 v[160:163], v80 offset:1024
	ds_read_b128 v[164:167], v80 offset:2048
	ds_read_b128 v[168:171], v80 offset:3072
	v_add_u32_e32 v80, s60, v144
	ds_read_b128 v[172:175], v80
	ds_read_b128 v[176:179], v80 offset:1024
	ds_read_b128 v[180:183], v80 offset:2048
	ds_read_b128 v[184:187], v80 offset:3072
	s_add_u32 s42, s48, 0xb0000
	s_addc_u32 s43, s49, 0
	s_mov_b32 m0, s30
	v_lshl_add_u64 v[240:241], s[42:43], 0, v[136:137]
	ds_read_b128 v[188:191], v145 offset:32768
	ds_read_b128 v[204:207], v145 offset:33792
	ds_read_b128 v[214:217], v145 offset:34816
	ds_read_b128 v[218:221], v145 offset:35840
	ds_read_b128 v[222:225], v145 offset:36864
	ds_read_b128 v[226:229], v145 offset:37888
	ds_read_b128 v[230:233], v145 offset:38912
	ds_read_b128 v[234:237], v145 offset:39936
	global_load_lds_dwordx4 v[240:241], off
	v_lshl_add_u64 v[240:241], s[42:43], 0, v[132:133]
	s_mov_b32 m0, s33
	s_nop 0
	global_load_lds_dwordx4 v[240:241], off
	s_waitcnt vmcnt(8)
	s_waitcnt lgkmcnt(0)
	s_barrier
	s_waitcnt lgkmcnt(0)
	v_mfma_f32_16x16x32_bf16 v[126:129], v[146:149], v[188:191], v[126:129]
	v_mfma_f32_16x16x32_bf16 v[122:125], v[164:167], v[188:191], v[122:125]
	v_mfma_f32_16x16x32_bf16 v[110:113], v[146:149], v[214:217], v[110:113]
	v_mfma_f32_16x16x32_bf16 v[106:109], v[164:167], v[214:217], v[106:109]
	v_mfma_f32_16x16x32_bf16 v[94:97], v[146:149], v[222:225], v[94:97]
	v_mfma_f32_16x16x32_bf16 v[90:93], v[164:167], v[222:225], v[90:93]
	v_mfma_f32_16x16x32_bf16 v[76:79], v[146:149], v[230:233], v[76:79]
	v_mfma_f32_16x16x32_bf16 v[72:75], v[164:167], v[230:233], v[72:75]
	v_mfma_f32_16x16x32_bf16 v[126:129], v[160:163], v[204:207], v[126:129]
	v_mfma_f32_16x16x32_bf16 v[122:125], v[168:171], v[204:207], v[122:125]
	v_mfma_f32_16x16x32_bf16 v[110:113], v[160:163], v[218:221], v[110:113]
	v_mfma_f32_16x16x32_bf16 v[106:109], v[168:171], v[218:221], v[106:109]
	v_mfma_f32_16x16x32_bf16 v[94:97], v[160:163], v[226:229], v[94:97]
	v_mfma_f32_16x16x32_bf16 v[90:93], v[168:171], v[226:229], v[90:93]
	v_mfma_f32_16x16x32_bf16 v[76:79], v[160:163], v[234:237], v[76:79]
	v_mfma_f32_16x16x32_bf16 v[72:75], v[168:171], v[234:237], v[72:75]
	v_mfma_f32_16x16x32_bf16 v[118:121], v[172:175], v[188:191], v[118:121]
	v_mfma_f32_16x16x32_bf16 v[114:117], v[180:183], v[188:191], v[114:117]
	v_mfma_f32_16x16x32_bf16 v[102:105], v[172:175], v[214:217], v[102:105]
	v_mfma_f32_16x16x32_bf16 v[98:101], v[180:183], v[214:217], v[98:101]
	v_mfma_f32_16x16x32_bf16 v[86:89], v[172:175], v[222:225], v[86:89]
	v_mfma_f32_16x16x32_bf16 v[82:85], v[180:183], v[222:225], v[82:85]
	v_mfma_f32_16x16x32_bf16 v[68:71], v[172:175], v[230:233], v[68:71]
	v_mfma_f32_16x16x32_bf16 v[64:67], v[180:183], v[230:233], v[64:67]
	v_mfma_f32_16x16x32_bf16 v[118:121], v[176:179], v[204:207], v[118:121]
	v_mfma_f32_16x16x32_bf16 v[114:117], v[184:187], v[204:207], v[114:117]
	v_mfma_f32_16x16x32_bf16 v[102:105], v[176:179], v[218:221], v[102:105]
	v_mfma_f32_16x16x32_bf16 v[98:101], v[184:187], v[218:221], v[98:101]
	v_mfma_f32_16x16x32_bf16 v[86:89], v[176:179], v[226:229], v[86:89]
	v_mfma_f32_16x16x32_bf16 v[82:85], v[184:187], v[226:229], v[82:85]
	v_mfma_f32_16x16x32_bf16 v[68:71], v[176:179], v[234:237], v[68:71]
	v_mfma_f32_16x16x32_bf16 v[64:67], v[184:187], v[234:237], v[64:67]
	s_barrier
	s_add_i32 s42, s57, s4
	v_lshl_add_u64 v[142:143], v[142:143], 0, s[20:21]
	s_mov_b32 m0, s42
	ds_read_b128 v[188:191], v145 offset:49152
	ds_read_b128 v[204:207], v145 offset:50176
	ds_read_b128 v[214:217], v145 offset:51200
	ds_read_b128 v[218:221], v145 offset:52224
	ds_read_b128 v[222:225], v145 offset:53248
	ds_read_b128 v[226:229], v145 offset:54272
	ds_read_b128 v[230:233], v145 offset:55296
	ds_read_b128 v[234:237], v145 offset:56320
	global_load_lds_dwordx4 v[142:143], off
	s_add_i32 m0, s42, 0x2000
	s_add_u32 s42, s46, 0xb0080
	v_lshl_add_u64 v[142:143], v[150:151], 0, s[20:21]
	s_addc_u32 s43, s47, 0
	s_add_i32 s46, s60, s4
	global_load_lds_dwordx4 v[142:143], off
	v_lshl_add_u64 v[142:143], s[42:43], 0, v[134:135]
	s_mov_b32 m0, s46
	s_nop 0
	global_load_lds_dwordx4 v[142:143], off
	v_lshl_add_u64 v[142:143], s[42:43], 0, v[130:131]
	s_add_i32 m0, s46, 0x2000
	s_nop 0
	global_load_lds_dwordx4 v[142:143], off
	v_lshl_add_u64 v[142:143], v[208:209], 0, s[20:21]
	s_mov_b32 m0, s34
	s_nop 0
	global_load_lds_dwordx4 v[142:143], off
	v_lshl_add_u64 v[142:143], v[238:239], 0, s[20:21]
	s_mov_b32 m0, s36
	s_nop 0
	global_load_lds_dwordx4 v[142:143], off
	s_waitcnt vmcnt(8)
	s_waitcnt lgkmcnt(0)
	s_barrier
	s_waitcnt lgkmcnt(0)
	v_mfma_f32_16x16x32_bf16 v[60:63], v[146:149], v[188:191], v[60:63]
	v_mfma_f32_16x16x32_bf16 v[56:59], v[164:167], v[188:191], v[56:59]
	v_mfma_f32_16x16x32_bf16 v[44:47], v[146:149], v[214:217], v[44:47]
	v_mfma_f32_16x16x32_bf16 v[40:43], v[164:167], v[214:217], v[40:43]
	v_mfma_f32_16x16x32_bf16 v[28:31], v[146:149], v[222:225], v[28:31]
	v_mfma_f32_16x16x32_bf16 v[24:27], v[164:167], v[222:225], v[24:27]
	v_mfma_f32_16x16x32_bf16 v[12:15], v[146:149], v[230:233], v[12:15]
	v_mfma_f32_16x16x32_bf16 v[8:11], v[164:167], v[230:233], v[8:11]
	v_mfma_f32_16x16x32_bf16 v[60:63], v[160:163], v[204:207], v[60:63]
	v_mfma_f32_16x16x32_bf16 v[56:59], v[168:171], v[204:207], v[56:59]
	v_mfma_f32_16x16x32_bf16 v[44:47], v[160:163], v[218:221], v[44:47]
	v_mfma_f32_16x16x32_bf16 v[40:43], v[168:171], v[218:221], v[40:43]
	v_mfma_f32_16x16x32_bf16 v[28:31], v[160:163], v[226:229], v[28:31]
	v_mfma_f32_16x16x32_bf16 v[24:27], v[168:171], v[226:229], v[24:27]
	v_mfma_f32_16x16x32_bf16 v[12:15], v[160:163], v[234:237], v[12:15]
	v_mfma_f32_16x16x32_bf16 v[8:11], v[168:171], v[234:237], v[8:11]
	v_mfma_f32_16x16x32_bf16 v[52:55], v[172:175], v[188:191], v[52:55]
	v_mfma_f32_16x16x32_bf16 v[48:51], v[180:183], v[188:191], v[48:51]
	v_mfma_f32_16x16x32_bf16 v[36:39], v[172:175], v[214:217], v[36:39]
	v_mfma_f32_16x16x32_bf16 v[32:35], v[180:183], v[214:217], v[32:35]
	v_mfma_f32_16x16x32_bf16 v[20:23], v[172:175], v[222:225], v[20:23]
	v_mfma_f32_16x16x32_bf16 v[16:19], v[180:183], v[222:225], v[16:19]
	v_mfma_f32_16x16x32_bf16 v[4:7], v[172:175], v[230:233], v[4:7]
	v_mfma_f32_16x16x32_bf16 v[0:3], v[180:183], v[230:233], v[0:3]
	v_mfma_f32_16x16x32_bf16 v[52:55], v[176:179], v[204:207], v[52:55]
	v_mfma_f32_16x16x32_bf16 v[48:51], v[184:187], v[204:207], v[48:51]
	v_mfma_f32_16x16x32_bf16 v[36:39], v[176:179], v[218:221], v[36:39]
	v_mfma_f32_16x16x32_bf16 v[32:35], v[184:187], v[218:221], v[32:35]
	v_mfma_f32_16x16x32_bf16 v[20:23], v[176:179], v[226:229], v[20:23]
	v_mfma_f32_16x16x32_bf16 v[16:19], v[184:187], v[226:229], v[16:19]
	v_mfma_f32_16x16x32_bf16 v[4:7], v[176:179], v[234:237], v[4:7]
	v_mfma_f32_16x16x32_bf16 v[0:3], v[184:187], v[234:237], v[0:3]
	s_barrier
	s_add_i32 s56, s56, 2
	s_add_u32 s54, s54, 0x100
	s_addc_u32 s55, s55, 0
	s_cmp_gt_u32 s56, 41
	s_mov_b64 s[42:43], s[44:45]
	s_cbranch_scc0 .LBB0_640
	s_and_b64 vcc, exec, s[6:7]
	s_cbranch_vccz .LBB0_643
	s_barrier

.LBB0_677:
	s_add_u32 s48, s46, 0xfffc0080
	s_addc_u32 s49, s47, -1
	s_add_i32 s61, 16, 0x10000
	s_cmp_eq_u32 s60, 12
	s_cselect_b32 s51, s15, s49
	s_cselect_b32 s50, s54, s48
	v_add_u32_e32 v80, s61, v146
	s_cselect_b32 s49, s11, s57
	s_cselect_b32 s48, s55, s56
	s_add_i32 s74, 16, 0x14000
	ds_read_b128 v[142:145], v80
	ds_read_b128 v[148:151], v80 offset:1024
	ds_read_b128 v[160:163], v80 offset:2048
	ds_read_b128 v[164:167], v80 offset:3072
	v_add_u32_e32 v80, s74, v146
	ds_read_b128 v[168:171], v80
	ds_read_b128 v[172:175], v80 offset:1024
	ds_read_b128 v[176:179], v80 offset:2048
	ds_read_b128 v[180:183], v80 offset:3072
	v_lshl_add_u64 v[208:209], s[46:47], 0, v[138:139]
	s_add_i32 m0, s13, 0xc000
	ds_read_b128 v[184:187], v147
	ds_read_b128 v[188:191], v147 offset:1024
	ds_read_b128 v[204:207], v147 offset:2048
	ds_read_b128 v[214:217], v147 offset:3072
	ds_read_b128 v[218:221], v147 offset:4096
	ds_read_b128 v[222:225], v147 offset:5120
	ds_read_b128 v[226:229], v147 offset:6144
	ds_read_b128 v[230:233], v147 offset:7168
	global_load_lds_dwordx4 v[208:209], off
	v_lshl_add_u64 v[208:209], s[46:47], 0, v[140:141]
	s_add_i32 m0, s13, 0xe000
	s_nop 0
	global_load_lds_dwordx4 v[208:209], off
	s_waitcnt vmcnt(8)
	s_waitcnt lgkmcnt(0)
	s_barrier
	s_waitcnt lgkmcnt(0)
	v_mfma_f32_16x16x32_bf16 v[126:129], v[142:145], v[184:187], v[126:129]
	v_mfma_f32_16x16x32_bf16 v[118:121], v[160:163], v[184:187], v[118:121]
	v_mfma_f32_16x16x32_bf16 v[110:113], v[142:145], v[204:207], v[110:113]
	v_mfma_f32_16x16x32_bf16 v[102:105], v[160:163], v[204:207], v[102:105]
	v_mfma_f32_16x16x32_bf16 v[94:97], v[142:145], v[218:221], v[94:97]
	v_mfma_f32_16x16x32_bf16 v[86:89], v[160:163], v[218:221], v[86:89]
	v_mfma_f32_16x16x32_bf16 v[76:79], v[142:145], v[226:229], v[76:79]
	v_mfma_f32_16x16x32_bf16 v[68:71], v[160:163], v[226:229], v[68:71]
	v_mfma_f32_16x16x32_bf16 v[126:129], v[148:151], v[188:191], v[126:129]
	v_mfma_f32_16x16x32_bf16 v[118:121], v[164:167], v[188:191], v[118:121]
	v_mfma_f32_16x16x32_bf16 v[110:113], v[148:151], v[214:217], v[110:113]
	v_mfma_f32_16x16x32_bf16 v[102:105], v[164:167], v[214:217], v[102:105]
	v_mfma_f32_16x16x32_bf16 v[94:97], v[148:151], v[222:225], v[94:97]
	v_mfma_f32_16x16x32_bf16 v[86:89], v[164:167], v[222:225], v[86:89]
	v_mfma_f32_16x16x32_bf16 v[76:79], v[148:151], v[230:233], v[76:79]
	v_mfma_f32_16x16x32_bf16 v[68:71], v[164:167], v[230:233], v[68:71]
	v_mfma_f32_16x16x32_bf16 v[122:125], v[168:171], v[184:187], v[122:125]
	v_mfma_f32_16x16x32_bf16 v[114:117], v[176:179], v[184:187], v[114:117]
	v_mfma_f32_16x16x32_bf16 v[106:109], v[168:171], v[204:207], v[106:109]
	v_mfma_f32_16x16x32_bf16 v[98:101], v[176:179], v[204:207], v[98:101]
	v_mfma_f32_16x16x32_bf16 v[90:93], v[168:171], v[218:221], v[90:93]
	v_mfma_f32_16x16x32_bf16 v[82:85], v[176:179], v[218:221], v[82:85]
	v_mfma_f32_16x16x32_bf16 v[72:75], v[168:171], v[226:229], v[72:75]
	v_mfma_f32_16x16x32_bf16 v[64:67], v[176:179], v[226:229], v[64:67]
	v_mfma_f32_16x16x32_bf16 v[122:125], v[172:175], v[188:191], v[122:125]
	v_mfma_f32_16x16x32_bf16 v[114:117], v[180:183], v[188:191], v[114:117]
	v_mfma_f32_16x16x32_bf16 v[106:109], v[172:175], v[214:217], v[106:109]
	v_mfma_f32_16x16x32_bf16 v[98:101], v[180:183], v[214:217], v[98:101]
	v_mfma_f32_16x16x32_bf16 v[90:93], v[172:175], v[222:225], v[90:93]
	v_mfma_f32_16x16x32_bf16 v[82:85], v[180:183], v[222:225], v[82:85]
	v_mfma_f32_16x16x32_bf16 v[72:75], v[172:175], v[230:233], v[72:75]
	v_mfma_f32_16x16x32_bf16 v[64:67], v[180:183], v[230:233], v[64:67]
	s_barrier
	s_add_i32 s61, s61, s4
	v_lshl_add_u64 v[208:209], s[48:49], 0, v[134:135]
	s_mov_b32 m0, s61
	ds_read_b128 v[184:187], v147 offset:16384
	ds_read_b128 v[188:191], v147 offset:17408
	ds_read_b128 v[204:207], v147 offset:18432
	ds_read_b128 v[214:217], v147 offset:19456
	ds_read_b128 v[218:221], v147 offset:20480
	ds_read_b128 v[222:225], v147 offset:21504
	ds_read_b128 v[226:229], v147 offset:22528
	ds_read_b128 v[230:233], v147 offset:23552
	global_load_lds_dwordx4 v[208:209], off
	s_add_i32 m0, s61, 0x2000
	s_add_u32 s66, s48, 0x40000
	v_lshl_add_u64 v[234:235], s[48:49], 0, v[130:131]
	s_addc_u32 s67, s49, 0
	s_add_i32 s61, s74, s4
	global_load_lds_dwordx4 v[234:235], off
	v_lshl_add_u64 v[236:237], s[66:67], 0, v[134:135]
	s_mov_b32 m0, s61
	v_lshl_add_u64 v[238:239], s[50:51], 0, v[132:133]
	global_load_lds_dwordx4 v[236:237], off
	v_lshl_add_u64 v[236:237], s[66:67], 0, v[130:131]
	s_add_i32 m0, s61, 0x2000
	s_nop 0
	global_load_lds_dwordx4 v[236:237], off
	v_lshl_add_u64 v[236:237], s[50:51], 0, v[136:137]
	s_mov_b32 m0, s13
	s_nop 0
	global_load_lds_dwordx4 v[236:237], off
	s_mov_b32 m0, s25
	s_nop 0
	global_load_lds_dwordx4 v[238:239], off
	s_waitcnt vmcnt(8)
	s_waitcnt lgkmcnt(0)
	s_barrier
	s_waitcnt lgkmcnt(0)
	v_mfma_f32_16x16x32_bf16 v[60:63], v[142:145], v[184:187], v[60:63]
	v_mfma_f32_16x16x32_bf16 v[52:55], v[160:163], v[184:187], v[52:55]
	v_mfma_f32_16x16x32_bf16 v[44:47], v[142:145], v[204:207], v[44:47]
	v_mfma_f32_16x16x32_bf16 v[36:39], v[160:163], v[204:207], v[36:39]
	v_mfma_f32_16x16x32_bf16 v[28:31], v[142:145], v[218:221], v[28:31]
	v_mfma_f32_16x16x32_bf16 v[20:23], v[160:163], v[218:221], v[20:23]
	v_mfma_f32_16x16x32_bf16 v[12:15], v[142:145], v[226:229], v[12:15]
	v_mfma_f32_16x16x32_bf16 v[4:7], v[160:163], v[226:229], v[4:7]
	v_mfma_f32_16x16x32_bf16 v[60:63], v[148:151], v[188:191], v[60:63]
	v_mfma_f32_16x16x32_bf16 v[52:55], v[164:167], v[188:191], v[52:55]
	v_mfma_f32_16x16x32_bf16 v[44:47], v[148:151], v[214:217], v[44:47]
	v_mfma_f32_16x16x32_bf16 v[36:39], v[164:167], v[214:217], v[36:39]
	v_mfma_f32_16x16x32_bf16 v[28:31], v[148:151], v[222:225], v[28:31]
	v_mfma_f32_16x16x32_bf16 v[20:23], v[164:167], v[222:225], v[20:23]
	v_mfma_f32_16x16x32_bf16 v[12:15], v[148:151], v[230:233], v[12:15]
	v_mfma_f32_16x16x32_bf16 v[4:7], v[164:167], v[230:233], v[4:7]
	v_mfma_f32_16x16x32_bf16 v[56:59], v[168:171], v[184:187], v[56:59]
	v_mfma_f32_16x16x32_bf16 v[48:51], v[176:179], v[184:187], v[48:51]
	v_mfma_f32_16x16x32_bf16 v[40:43], v[168:171], v[204:207], v[40:43]
	v_mfma_f32_16x16x32_bf16 v[32:35], v[176:179], v[204:207], v[32:35]
	v_mfma_f32_16x16x32_bf16 v[24:27], v[168:171], v[218:221], v[24:27]
	v_mfma_f32_16x16x32_bf16 v[16:19], v[176:179], v[218:221], v[16:19]
	v_mfma_f32_16x16x32_bf16 v[8:11], v[168:171], v[226:229], v[8:11]
	v_mfma_f32_16x16x32_bf16 v[0:3], v[176:179], v[226:229], v[0:3]
	v_mfma_f32_16x16x32_bf16 v[56:59], v[172:175], v[188:191], v[56:59]
	v_mfma_f32_16x16x32_bf16 v[48:51], v[180:183], v[188:191], v[48:51]
	v_mfma_f32_16x16x32_bf16 v[40:43], v[172:175], v[214:217], v[40:43]
	v_mfma_f32_16x16x32_bf16 v[32:35], v[180:183], v[214:217], v[32:35]
	v_mfma_f32_16x16x32_bf16 v[24:27], v[172:175], v[222:225], v[24:27]
	v_mfma_f32_16x16x32_bf16 v[16:19], v[180:183], v[222:225], v[16:19]
	v_mfma_f32_16x16x32_bf16 v[8:11], v[172:175], v[230:233], v[8:11]
	v_mfma_f32_16x16x32_bf16 v[0:3], v[180:183], v[230:233], v[0:3]
	s_barrier
	s_add_i32 s61, 16, 0x18000
	v_add_u32_e32 v80, s61, v146
	s_add_i32 s66, 16, 0x1c000
	ds_read_b128 v[142:145], v80
	ds_read_b128 v[148:151], v80 offset:1024
	ds_read_b128 v[160:163], v80 offset:2048
	ds_read_b128 v[164:167], v80 offset:3072
	v_add_u32_e32 v80, s66, v146
	ds_read_b128 v[168:171], v80
	ds_read_b128 v[172:175], v80 offset:1024
	ds_read_b128 v[176:179], v80 offset:2048
	ds_read_b128 v[180:183], v80 offset:3072
	s_add_u32 s50, s50, 0x40000
	s_addc_u32 s51, s51, 0
	s_mov_b32 m0, s30
	v_lshl_add_u64 v[240:241], s[50:51], 0, v[136:137]
	ds_read_b128 v[184:187], v147 offset:32768
	ds_read_b128 v[188:191], v147 offset:33792
	ds_read_b128 v[204:207], v147 offset:34816
	ds_read_b128 v[214:217], v147 offset:35840
	ds_read_b128 v[218:221], v147 offset:36864
	ds_read_b128 v[222:225], v147 offset:37888
	ds_read_b128 v[226:229], v147 offset:38912
	ds_read_b128 v[230:233], v147 offset:39936
	global_load_lds_dwordx4 v[240:241], off
	v_lshl_add_u64 v[240:241], s[50:51], 0, v[132:133]
	s_mov_b32 m0, s33
	s_nop 0
	global_load_lds_dwordx4 v[240:241], off
	s_waitcnt vmcnt(8)
	s_waitcnt lgkmcnt(0)
	s_barrier
	s_waitcnt lgkmcnt(0)
	v_mfma_f32_16x16x32_bf16 v[126:129], v[142:145], v[184:187], v[126:129]
	v_mfma_f32_16x16x32_bf16 v[118:121], v[160:163], v[184:187], v[118:121]
	v_mfma_f32_16x16x32_bf16 v[110:113], v[142:145], v[204:207], v[110:113]
	v_mfma_f32_16x16x32_bf16 v[102:105], v[160:163], v[204:207], v[102:105]
	v_mfma_f32_16x16x32_bf16 v[94:97], v[142:145], v[218:221], v[94:97]
	v_mfma_f32_16x16x32_bf16 v[86:89], v[160:163], v[218:221], v[86:89]
	v_mfma_f32_16x16x32_bf16 v[76:79], v[142:145], v[226:229], v[76:79]
	v_mfma_f32_16x16x32_bf16 v[68:71], v[160:163], v[226:229], v[68:71]
	v_mfma_f32_16x16x32_bf16 v[126:129], v[148:151], v[188:191], v[126:129]
	v_mfma_f32_16x16x32_bf16 v[118:121], v[164:167], v[188:191], v[118:121]
	v_mfma_f32_16x16x32_bf16 v[110:113], v[148:151], v[214:217], v[110:113]
	v_mfma_f32_16x16x32_bf16 v[102:105], v[164:167], v[214:217], v[102:105]
	v_mfma_f32_16x16x32_bf16 v[94:97], v[148:151], v[222:225], v[94:97]
	v_mfma_f32_16x16x32_bf16 v[86:89], v[164:167], v[222:225], v[86:89]
	v_mfma_f32_16x16x32_bf16 v[76:79], v[148:151], v[230:233], v[76:79]
	v_mfma_f32_16x16x32_bf16 v[68:71], v[164:167], v[230:233], v[68:71]
	v_mfma_f32_16x16x32_bf16 v[122:125], v[168:171], v[184:187], v[122:125]
	v_mfma_f32_16x16x32_bf16 v[114:117], v[176:179], v[184:187], v[114:117]
	v_mfma_f32_16x16x32_bf16 v[106:109], v[168:171], v[204:207], v[106:109]
	v_mfma_f32_16x16x32_bf16 v[98:101], v[176:179], v[204:207], v[98:101]
	v_mfma_f32_16x16x32_bf16 v[90:93], v[168:171], v[218:221], v[90:93]
	v_mfma_f32_16x16x32_bf16 v[82:85], v[176:179], v[218:221], v[82:85]
	v_mfma_f32_16x16x32_bf16 v[72:75], v[168:171], v[226:229], v[72:75]
	v_mfma_f32_16x16x32_bf16 v[64:67], v[176:179], v[226:229], v[64:67]
	v_mfma_f32_16x16x32_bf16 v[122:125], v[172:175], v[188:191], v[122:125]
	v_mfma_f32_16x16x32_bf16 v[114:117], v[180:183], v[188:191], v[114:117]
	v_mfma_f32_16x16x32_bf16 v[106:109], v[172:175], v[214:217], v[106:109]
	v_mfma_f32_16x16x32_bf16 v[98:101], v[180:183], v[214:217], v[98:101]
	v_mfma_f32_16x16x32_bf16 v[90:93], v[172:175], v[222:225], v[90:93]
	v_mfma_f32_16x16x32_bf16 v[82:85], v[180:183], v[222:225], v[82:85]
	v_mfma_f32_16x16x32_bf16 v[72:75], v[172:175], v[230:233], v[72:75]
	v_mfma_f32_16x16x32_bf16 v[64:67], v[180:183], v[230:233], v[64:67]
	s_barrier
	s_add_i32 s50, s61, s4
	v_lshl_add_u64 v[208:209], v[208:209], 0, s[20:21]
	s_mov_b32 m0, s50
	ds_read_b128 v[184:187], v147 offset:49152
	ds_read_b128 v[188:191], v147 offset:50176
	ds_read_b128 v[204:207], v147 offset:51200
	ds_read_b128 v[214:217], v147 offset:52224
	ds_read_b128 v[218:221], v147 offset:53248
	ds_read_b128 v[222:225], v147 offset:54272
	ds_read_b128 v[226:229], v147 offset:55296
	ds_read_b128 v[230:233], v147 offset:56320
	global_load_lds_dwordx4 v[208:209], off
	s_add_i32 m0, s50, 0x2000
	s_add_u32 s48, s48, 0x40080
	v_lshl_add_u64 v[208:209], v[234:235], 0, s[20:21]
	s_addc_u32 s49, s49, 0
	s_add_i32 s50, s66, s4
	global_load_lds_dwordx4 v[208:209], off
	v_lshl_add_u64 v[208:209], s[48:49], 0, v[134:135]
	s_mov_b32 m0, s50
	s_nop 0
	global_load_lds_dwordx4 v[208:209], off
	v_lshl_add_u64 v[208:209], s[48:49], 0, v[130:131]
	s_add_i32 m0, s50, 0x2000
	s_nop 0
	global_load_lds_dwordx4 v[208:209], off
	v_lshl_add_u64 v[208:209], v[236:237], 0, s[20:21]
	s_mov_b32 m0, s34
	s_nop 0
	global_load_lds_dwordx4 v[208:209], off
	v_lshl_add_u64 v[208:209], v[238:239], 0, s[20:21]
	s_mov_b32 m0, s36
	s_nop 0
	global_load_lds_dwordx4 v[208:209], off
	s_waitcnt vmcnt(8)
	s_waitcnt lgkmcnt(0)
	s_barrier
	s_waitcnt lgkmcnt(0)
	v_mfma_f32_16x16x32_bf16 v[60:63], v[142:145], v[184:187], v[60:63]
	v_mfma_f32_16x16x32_bf16 v[52:55], v[160:163], v[184:187], v[52:55]
	v_mfma_f32_16x16x32_bf16 v[44:47], v[142:145], v[204:207], v[44:47]
	v_mfma_f32_16x16x32_bf16 v[36:39], v[160:163], v[204:207], v[36:39]
	v_mfma_f32_16x16x32_bf16 v[28:31], v[142:145], v[218:221], v[28:31]
	v_mfma_f32_16x16x32_bf16 v[20:23], v[160:163], v[218:221], v[20:23]
	v_mfma_f32_16x16x32_bf16 v[12:15], v[142:145], v[226:229], v[12:15]
	v_mfma_f32_16x16x32_bf16 v[4:7], v[160:163], v[226:229], v[4:7]
	v_mfma_f32_16x16x32_bf16 v[60:63], v[148:151], v[188:191], v[60:63]
	v_mfma_f32_16x16x32_bf16 v[52:55], v[164:167], v[188:191], v[52:55]
	v_mfma_f32_16x16x32_bf16 v[44:47], v[148:151], v[214:217], v[44:47]
	v_mfma_f32_16x16x32_bf16 v[36:39], v[164:167], v[214:217], v[36:39]
	v_mfma_f32_16x16x32_bf16 v[28:31], v[148:151], v[222:225], v[28:31]
	v_mfma_f32_16x16x32_bf16 v[20:23], v[164:167], v[222:225], v[20:23]
	v_mfma_f32_16x16x32_bf16 v[12:15], v[148:151], v[230:233], v[12:15]
	v_mfma_f32_16x16x32_bf16 v[4:7], v[164:167], v[230:233], v[4:7]
	v_mfma_f32_16x16x32_bf16 v[56:59], v[168:171], v[184:187], v[56:59]
	v_mfma_f32_16x16x32_bf16 v[48:51], v[176:179], v[184:187], v[48:51]
	v_mfma_f32_16x16x32_bf16 v[40:43], v[168:171], v[204:207], v[40:43]
	v_mfma_f32_16x16x32_bf16 v[32:35], v[176:179], v[204:207], v[32:35]
	v_mfma_f32_16x16x32_bf16 v[24:27], v[168:171], v[218:221], v[24:27]
	v_mfma_f32_16x16x32_bf16 v[16:19], v[176:179], v[218:221], v[16:19]
	v_mfma_f32_16x16x32_bf16 v[8:11], v[168:171], v[226:229], v[8:11]
	v_mfma_f32_16x16x32_bf16 v[0:3], v[176:179], v[226:229], v[0:3]
	v_mfma_f32_16x16x32_bf16 v[56:59], v[172:175], v[188:191], v[56:59]
	v_mfma_f32_16x16x32_bf16 v[48:51], v[180:183], v[188:191], v[48:51]
	v_mfma_f32_16x16x32_bf16 v[40:43], v[172:175], v[214:217], v[40:43]
	v_mfma_f32_16x16x32_bf16 v[32:35], v[180:183], v[214:217], v[32:35]
	v_mfma_f32_16x16x32_bf16 v[24:27], v[172:175], v[222:225], v[24:27]
	v_mfma_f32_16x16x32_bf16 v[16:19], v[180:183], v[222:225], v[16:19]
	v_mfma_f32_16x16x32_bf16 v[8:11], v[172:175], v[230:233], v[8:11]
	v_mfma_f32_16x16x32_bf16 v[0:3], v[180:183], v[230:233], v[0:3]
	s_barrier
	s_add_i32 s60, s60, 2
	s_add_u32 s46, s46, 0x100
	s_addc_u32 s47, s47, 0
	s_add_u32 s56, s56, 0x100
	s_addc_u32 s57, s57, 0
	s_cmp_gt_u32 s60, 13
	s_cbranch_scc0 .LBB0_677
	v_mov_b32_e32 v150, v192
	s_lshl_b32 s11, s53, 8
	v_mov_b32_e32 v148, v122
	v_ashrrev_i32_e32 v80, 2, v150
	v_and_b32_e32 v80, 0xffffffc0, v80
	v_and_or_b32 v142, v150, 15, s11
	v_add_u32_e32 v142, v142, v80
	v_ashrrev_i32_e32 v143, 31, v142
	v_lshl_add_u64 v[144:145], v[142:143], 2, s[90:91]
	global_load_dword v242, v[144:145], off
	global_load_dword v243, v[144:145], off offset:64
	global_load_dword v244, v[144:145], off offset:128
	global_load_dword v245, v[144:145], off offset:192
	global_load_dword v246, v[144:145], off offset:512
	global_load_dword v247, v[144:145], off offset:576
	global_load_dword v248, v[144:145], off offset:640
	global_load_dword v249, v[144:145], off offset:704
	s_and_b64 vcc, exec, s[6:7]
	s_cbranch_vccz .LBB0_680
	s_barrier
